# GEMM K-loops: load-segment half at priority 1, MFMA-block half at priority 0 (inverse of the baseline's per-block flips); stacked on stack18
# baseline (speedup 1.0000x reference)
; #define PG8_STAGE(bufoff, gbase, voff) do { _Pragma("unroll") for (int _i = 0; _i < 2; ++_i) \
;         __builtin_amdgcn_global_load_lds((const unsigned*)((const char*)(gbase) + (voff)[_i]), (PG8_LAS unsigned*)(lds + (bufoff) + ldsw + _i * 8192), 16, 0, 0); } while (0)
; #define PG8_LDA(dst, b, h) do { _Pragma("unroll") for (int m = 0; m < 4; ++m) _Pragma("unroll") for (int k = 0; k < 2; ++k) dst[m][k] = *(const PG8_LAS bf16x8*)(lds + PG8_SA(b, h) + aoff + m * 2048 + k * 1024); } while (0)
; #define PG8_LDB(dst, b, h) do { _Pragma("unroll") for (int n = 0; n < 2; ++n) _Pragma("unroll") for (int k = 0; k < 2; ++k) dst[n][k] = *(const PG8_LAS bf16x8*)(lds + PG8_SB(b, h) + boff + n * 2048 + k * 1024); } while (0)
; #define PG8_MMA(ai, bj, At, Bt) do { __builtin_amdgcn_s_setprio(1); _Pragma("unroll") for (int m = 0; m < 4; ++m) _Pragma("unroll") for (int n = 0; n < 2; ++n) _Pragma("unroll") for (int k = 0; k < 2; ++k) \
;         acc[ai][bj][m][n] = __builtin_amdgcn_mfma_f32_16x16x32_bf16(Bt[n][k], At[m][k], acc[ai][bj][m][n], 0, 0, 0); __builtin_amdgcn_s_setprio(0); } while (0)
; #define PG8_WAIT_V(n) asm volatile("s_waitcnt vmcnt(" #n ")" ::: "memory")
; #define PG8_WAIT_L(n) asm volatile("s_waitcnt lgkmcnt(" #n ")" ::: "memory")
; #define PG8_BAR __builtin_amdgcn_s_barrier()
; #define PG8_SCHED __builtin_amdgcn_sched_barrier(0)
; template <class Epi, class Sched, bool ALIGN_EPI = false, bool SP2 = false>
; __device__ __forceinline__ void gemm_phase(PG8_LAS unsigned char* lds, const Gemm g, const Sched& S, const Epi& E) {
;     ...
;             PG8_LDB(B0, 0, 0); PG8_LDB(B1, 0, 1); PG8_SCHED; PG8_LDA(At, 0, 0); PG8_STAGE(PG8_SA(1, 1), a1 + hstep, voffA);
;             PG8_WAIT_V(8); PG8_WAIT_L(0); PG8_BAR; PG8_MMA(0, 0, At, B0); PG8_MMA(0, 1, At, B1); PG8_BAR; PG8_SCHED;
;             PG8_LDA(At, 0, 1); PG8_STAGE(PG8_SB(0, 0), b2, voffB); PG8_STAGE(PG8_SB(0, 1), b2 + hstep, voffB); PG8_STAGE(PG8_SA(0, 0), a2, voffA);
;             PG8_WAIT_V(8); PG8_WAIT_L(0); PG8_BAR; PG8_MMA(1, 0, At, B0); PG8_MMA(1, 1, At, B1); PG8_BAR; PG8_SCHED;
;             PG8_LDB(B0, 1, 0); PG8_LDB(B1, 1, 1); PG8_SCHED; PG8_LDA(At, 1, 0); PG8_STAGE(PG8_SA(0, 1), a2 + hstep, voffA);
.LBB0_164:
	s_add_u32 s58, s72, 0xfffc0080
	s_addc_u32 s59, s73, -1
	s_add_i32 s84, 0, 0x10000
	s_cmp_eq_u32 s94, 12
	s_cselect_b32 s65, s36, s59
	s_cselect_b32 s64, s37, s58
	v_add_u32_e32 v140, s84, v146
	s_cselect_b32 s59, s51, s93
	s_cselect_b32 s58, s53, s92
	s_add_i32 s96, 0, 0x14000
	ds_read_b128 v[142:145], v140
	ds_read_b128 v[150:153], v140 offset:1024
	ds_read_b128 v[154:157], v140 offset:2048
	ds_read_b128 v[158:161], v140 offset:3072
	v_add_u32_e32 v140, s96, v146
	ds_read_b128 v[162:165], v140
	ds_read_b128 v[166:169], v140 offset:1024
	ds_read_b128 v[170:173], v140 offset:2048
	ds_read_b128 v[174:177], v140 offset:3072
	v_lshl_add_u64 v[186:187], s[72:73], 0, v[136:137]
	s_add_i32 m0, s19, 0xc000
	ds_read_b128 v[178:181], v148
	ds_read_b128 v[182:185], v148 offset:1024
	ds_read_b128 v[190:193], v148 offset:2048
	ds_read_b128 v[194:197], v148 offset:3072
	ds_read_b128 v[198:201], v148 offset:4096
	ds_read_b128 v[202:205], v148 offset:5120
	ds_read_b128 v[206:209], v148 offset:6144
	ds_read_b128 v[228:231], v148 offset:7168
	global_load_lds_dwordx4 v[186:187], off
	v_lshl_add_u64 v[186:187], s[72:73], 0, v[138:139]
	s_add_i32 m0, s19, 0xe000
	s_nop 0
	global_load_lds_dwordx4 v[186:187], off
	s_waitcnt vmcnt(8)
	s_waitcnt lgkmcnt(0)
	s_barrier
	s_setprio 0
	s_waitcnt lgkmcnt(0)
	v_mfma_f32_16x16x32_bf16 v[124:127], v[142:145], v[178:181], v[124:127]
	v_mfma_f32_16x16x32_bf16 v[120:123], v[154:157], v[178:181], v[120:123]
	v_mfma_f32_16x16x32_bf16 v[116:119], v[142:145], v[190:193], v[116:119]
	v_mfma_f32_16x16x32_bf16 v[112:115], v[154:157], v[190:193], v[112:115]
	v_mfma_f32_16x16x32_bf16 v[108:111], v[142:145], v[198:201], v[108:111]
	v_mfma_f32_16x16x32_bf16 v[104:107], v[154:157], v[198:201], v[104:107]
	v_mfma_f32_16x16x32_bf16 v[100:103], v[142:145], v[206:209], v[100:103]
	v_mfma_f32_16x16x32_bf16 v[96:99], v[154:157], v[206:209], v[96:99]
	v_mfma_f32_16x16x32_bf16 v[124:127], v[150:153], v[182:185], v[124:127]
	v_mfma_f32_16x16x32_bf16 v[120:123], v[158:161], v[182:185], v[120:123]
	v_mfma_f32_16x16x32_bf16 v[116:119], v[150:153], v[194:197], v[116:119]
	v_mfma_f32_16x16x32_bf16 v[112:115], v[158:161], v[194:197], v[112:115]
	v_mfma_f32_16x16x32_bf16 v[108:111], v[150:153], v[202:205], v[108:111]
	v_mfma_f32_16x16x32_bf16 v[104:107], v[158:161], v[202:205], v[104:107]
	v_mfma_f32_16x16x32_bf16 v[100:103], v[150:153], v[228:231], v[100:103]
	v_mfma_f32_16x16x32_bf16 v[96:99], v[158:161], v[228:231], v[96:99]
	v_mfma_f32_16x16x32_bf16 v[92:95], v[162:165], v[178:181], v[92:95]
	v_mfma_f32_16x16x32_bf16 v[88:91], v[170:173], v[178:181], v[88:91]
	v_mfma_f32_16x16x32_bf16 v[84:87], v[162:165], v[190:193], v[84:87]
	v_mfma_f32_16x16x32_bf16 v[80:83], v[170:173], v[190:193], v[80:83]
	v_mfma_f32_16x16x32_bf16 v[76:79], v[162:165], v[198:201], v[76:79]
	v_mfma_f32_16x16x32_bf16 v[72:75], v[170:173], v[198:201], v[72:75]
	v_mfma_f32_16x16x32_bf16 v[68:71], v[162:165], v[206:209], v[68:71]
	v_mfma_f32_16x16x32_bf16 v[64:67], v[170:173], v[206:209], v[64:67]
	v_mfma_f32_16x16x32_bf16 v[92:95], v[166:169], v[182:185], v[92:95]
	v_mfma_f32_16x16x32_bf16 v[88:91], v[174:177], v[182:185], v[88:91]
	v_mfma_f32_16x16x32_bf16 v[84:87], v[166:169], v[194:197], v[84:87]
	v_mfma_f32_16x16x32_bf16 v[80:83], v[174:177], v[194:197], v[80:83]
	v_mfma_f32_16x16x32_bf16 v[76:79], v[166:169], v[202:205], v[76:79]
	v_mfma_f32_16x16x32_bf16 v[72:75], v[174:177], v[202:205], v[72:75]
	v_mfma_f32_16x16x32_bf16 v[68:71], v[166:169], v[228:231], v[68:71]
	v_mfma_f32_16x16x32_bf16 v[64:67], v[174:177], v[228:231], v[64:67]
	s_barrier
	s_setprio 1
	s_add_i32 s84, s84, s18
	v_lshl_add_u64 v[186:187], s[58:59], 0, v[128:129]
	s_mov_b32 m0, s84
	ds_read_b128 v[178:181], v148 offset:16384
	ds_read_b128 v[182:185], v148 offset:17408
	ds_read_b128 v[190:193], v148 offset:18432
	ds_read_b128 v[194:197], v148 offset:19456
	ds_read_b128 v[198:201], v148 offset:20480
	ds_read_b128 v[202:205], v148 offset:21504
	ds_read_b128 v[206:209], v148 offset:22528
	ds_read_b128 v[228:231], v148 offset:23552
	global_load_lds_dwordx4 v[186:187], off
	s_add_i32 m0, s84, 0x2000
	s_add_u32 s84, s58, 0x40000
	v_lshl_add_u64 v[188:189], s[58:59], 0, v[130:131]
	s_addc_u32 s85, s59, 0
	s_add_i32 s96, s96, s18
	global_load_lds_dwordx4 v[188:189], off
	v_lshl_add_u64 v[210:211], s[84:85], 0, v[128:129]
	s_mov_b32 m0, s96
	v_lshl_add_u64 v[232:233], s[64:65], 0, v[132:133]
	global_load_lds_dwordx4 v[210:211], off
	v_lshl_add_u64 v[210:211], s[84:85], 0, v[130:131]
	s_add_i32 m0, s96, 0x2000
	s_nop 0
	global_load_lds_dwordx4 v[210:211], off
	v_lshl_add_u64 v[210:211], s[64:65], 0, v[134:135]
	s_mov_b32 m0, s19
	s_nop 0
	global_load_lds_dwordx4 v[210:211], off
	s_mov_b32 m0, s20
	s_nop 0
	global_load_lds_dwordx4 v[232:233], off
	s_waitcnt vmcnt(8)
	s_waitcnt lgkmcnt(0)
	s_barrier
; #define PG8_STAGE(bufoff, gbase, voff) do { _Pragma("unroll") for (int _i = 0; _i < 2; ++_i) \
;         __builtin_amdgcn_global_load_lds((const unsigned*)((const char*)(gbase) + (voff)[_i]), (PG8_LAS unsigned*)(lds + (bufoff) + ldsw + _i * 8192), 16, 0, 0); } while (0)
; #define PG8_LDA(dst, b, h) do { _Pragma("unroll") for (int m = 0; m < 4; ++m) _Pragma("unroll") for (int k = 0; k < 2; ++k) dst[m][k] = *(const PG8_LAS bf16x8*)(lds + PG8_SA(b, h) + aoff + m * 2048 + k * 1024); } while (0)
; #define PG8_LDB(dst, b, h) do { _Pragma("unroll") for (int n = 0; n < 2; ++n) _Pragma("unroll") for (int k = 0; k < 2; ++k) dst[n][k] = *(const PG8_LAS bf16x8*)(lds + PG8_SB(b, h) + boff + n * 2048 + k * 1024); } while (0)
; #define PG8_MMA(ai, bj, At, Bt) do { __builtin_amdgcn_s_setprio(1); _Pragma("unroll") for (int m = 0; m < 4; ++m) _Pragma("unroll") for (int n = 0; n < 2; ++n) _Pragma("unroll") for (int k = 0; k < 2; ++k) \
;         acc[ai][bj][m][n] = __builtin_amdgcn_mfma_f32_16x16x32_bf16(Bt[n][k], At[m][k], acc[ai][bj][m][n], 0, 0, 0); __builtin_amdgcn_s_setprio(0); } while (0)
; #define PG8_WAIT_V(n) asm volatile("s_waitcnt vmcnt(" #n ")" ::: "memory")
; template <class Epi, class Sched, bool ALIGN_EPI = false, bool SP2 = false>
; __device__ __forceinline__ void gemm_phase(PG8_LAS unsigned char* lds, const Gemm g, const Sched& S, const Epi& E) {
;     ...
;             PG8_LDB(B0, 0, 0); PG8_LDB(B1, 0, 1); PG8_SCHED; PG8_LDA(At, 0, 0); PG8_STAGE(PG8_SA(1, 1), a1 + hstep, voffA);
;             PG8_WAIT_V(8); PG8_WAIT_L(0); PG8_BAR; PG8_MMA(0, 0, At, B0); PG8_MMA(0, 1, At, B1); PG8_BAR; PG8_SCHED;
;             PG8_LDA(At, 0, 1); PG8_STAGE(PG8_SB(0, 0), b2, voffB); PG8_STAGE(PG8_SB(0, 1), b2 + hstep, voffB); PG8_STAGE(PG8_SA(0, 0), a2, voffA);
;             PG8_WAIT_V(8); PG8_WAIT_L(0); PG8_BAR; PG8_MMA(1, 0, At, B0); PG8_MMA(1, 1, At, B1); PG8_BAR; PG8_SCHED;
;             PG8_LDB(B0, 1, 0); PG8_LDB(B1, 1, 1); PG8_SCHED; PG8_LDA(At, 1, 0); PG8_STAGE(PG8_SA(0, 1), a2 + hstep, voffA);
;             PG8_WAIT_V(8); PG8_WAIT_L(0); PG8_BAR; PG8_MMA(0, 0, At, B0); PG8_MMA(0, 1, At, B1); PG8_BAR; PG8_SCHED;
;             PG8_LDA(At, 1, 1); PG8_STAGE(PG8_SB(1, 0), b3, voffB); PG8_STAGE(PG8_SB(1, 1), b3 + hstep, voffB); PG8_STAGE(PG8_SA(1, 0), a3, voffA);
;             PG8_WAIT_V(8); PG8_WAIT_L(0); PG8_BAR; PG8_MMA(1, 0, At, B0); PG8_MMA(1, 1, At, B1); PG8_BAR; PG8_SCHED;
	s_setprio 0
	s_waitcnt lgkmcnt(0)
	v_mfma_f32_16x16x32_bf16 v[60:63], v[142:145], v[178:181], v[60:63]
	v_mfma_f32_16x16x32_bf16 v[56:59], v[154:157], v[178:181], v[56:59]
	v_mfma_f32_16x16x32_bf16 v[52:55], v[142:145], v[190:193], v[52:55]
	v_mfma_f32_16x16x32_bf16 v[48:51], v[154:157], v[190:193], v[48:51]
	v_mfma_f32_16x16x32_bf16 v[44:47], v[142:145], v[198:201], v[44:47]
	v_mfma_f32_16x16x32_bf16 v[40:43], v[154:157], v[198:201], v[40:43]
	v_mfma_f32_16x16x32_bf16 v[36:39], v[142:145], v[206:209], v[36:39]
	v_mfma_f32_16x16x32_bf16 v[32:35], v[154:157], v[206:209], v[32:35]
	v_mfma_f32_16x16x32_bf16 v[60:63], v[150:153], v[182:185], v[60:63]
	v_mfma_f32_16x16x32_bf16 v[56:59], v[158:161], v[182:185], v[56:59]
	v_mfma_f32_16x16x32_bf16 v[52:55], v[150:153], v[194:197], v[52:55]
	v_mfma_f32_16x16x32_bf16 v[48:51], v[158:161], v[194:197], v[48:51]
	v_mfma_f32_16x16x32_bf16 v[44:47], v[150:153], v[202:205], v[44:47]
	v_mfma_f32_16x16x32_bf16 v[40:43], v[158:161], v[202:205], v[40:43]
	v_mfma_f32_16x16x32_bf16 v[36:39], v[150:153], v[228:231], v[36:39]
	v_mfma_f32_16x16x32_bf16 v[32:35], v[158:161], v[228:231], v[32:35]
	v_mfma_f32_16x16x32_bf16 v[28:31], v[162:165], v[178:181], v[28:31]
	v_mfma_f32_16x16x32_bf16 v[24:27], v[170:173], v[178:181], v[24:27]
	v_mfma_f32_16x16x32_bf16 v[20:23], v[162:165], v[190:193], v[20:23]
	v_mfma_f32_16x16x32_bf16 v[16:19], v[170:173], v[190:193], v[16:19]
	v_mfma_f32_16x16x32_bf16 v[12:15], v[162:165], v[198:201], v[12:15]
	v_mfma_f32_16x16x32_bf16 v[8:11], v[170:173], v[198:201], v[8:11]
	v_mfma_f32_16x16x32_bf16 v[4:7], v[162:165], v[206:209], v[4:7]
	v_mfma_f32_16x16x32_bf16 v[0:3], v[170:173], v[206:209], v[0:3]
	v_mfma_f32_16x16x32_bf16 v[28:31], v[166:169], v[182:185], v[28:31]
	v_mfma_f32_16x16x32_bf16 v[24:27], v[174:177], v[182:185], v[24:27]
	v_mfma_f32_16x16x32_bf16 v[20:23], v[166:169], v[194:197], v[20:23]
	v_mfma_f32_16x16x32_bf16 v[16:19], v[174:177], v[194:197], v[16:19]
	v_mfma_f32_16x16x32_bf16 v[12:15], v[166:169], v[202:205], v[12:15]
	v_mfma_f32_16x16x32_bf16 v[8:11], v[174:177], v[202:205], v[8:11]
	v_mfma_f32_16x16x32_bf16 v[4:7], v[166:169], v[228:231], v[4:7]
	v_mfma_f32_16x16x32_bf16 v[0:3], v[174:177], v[228:231], v[0:3]
	s_barrier
	s_setprio 1
	s_add_i32 s84, 0, 0x18000
	v_add_u32_e32 v140, s84, v146
	s_add_i32 s85, 0, 0x1c000
	ds_read_b128 v[142:145], v140
	ds_read_b128 v[150:153], v140 offset:1024
	ds_read_b128 v[154:157], v140 offset:2048
	ds_read_b128 v[158:161], v140 offset:3072
	v_add_u32_e32 v140, s85, v146
	ds_read_b128 v[162:165], v140
	ds_read_b128 v[166:169], v140 offset:1024
	ds_read_b128 v[170:173], v140 offset:2048
	ds_read_b128 v[174:177], v140 offset:3072
	s_add_u32 s64, s64, 0x40000
	s_addc_u32 s65, s65, 0
	s_mov_b32 m0, s21
	v_lshl_add_u64 v[234:235], s[64:65], 0, v[134:135]
	ds_read_b128 v[178:181], v148 offset:32768
	ds_read_b128 v[182:185], v148 offset:33792
	ds_read_b128 v[190:193], v148 offset:34816
	ds_read_b128 v[194:197], v148 offset:35840
	ds_read_b128 v[198:201], v148 offset:36864
	ds_read_b128 v[202:205], v148 offset:37888
	ds_read_b128 v[206:209], v148 offset:38912
	ds_read_b128 v[228:231], v148 offset:39936
	global_load_lds_dwordx4 v[234:235], off
	v_lshl_add_u64 v[234:235], s[64:65], 0, v[132:133]
	s_mov_b32 m0, s22
	s_nop 0
	global_load_lds_dwordx4 v[234:235], off
	s_waitcnt vmcnt(8)
	s_waitcnt lgkmcnt(0)
	s_barrier
	s_setprio 0
	s_waitcnt lgkmcnt(0)
	v_mfma_f32_16x16x32_bf16 v[124:127], v[142:145], v[178:181], v[124:127]
	v_mfma_f32_16x16x32_bf16 v[120:123], v[154:157], v[178:181], v[120:123]
	v_mfma_f32_16x16x32_bf16 v[116:119], v[142:145], v[190:193], v[116:119]
	v_mfma_f32_16x16x32_bf16 v[112:115], v[154:157], v[190:193], v[112:115]
	v_mfma_f32_16x16x32_bf16 v[108:111], v[142:145], v[198:201], v[108:111]
	v_mfma_f32_16x16x32_bf16 v[104:107], v[154:157], v[198:201], v[104:107]
	v_mfma_f32_16x16x32_bf16 v[100:103], v[142:145], v[206:209], v[100:103]
	v_mfma_f32_16x16x32_bf16 v[96:99], v[154:157], v[206:209], v[96:99]
	v_mfma_f32_16x16x32_bf16 v[124:127], v[150:153], v[182:185], v[124:127]
	v_mfma_f32_16x16x32_bf16 v[120:123], v[158:161], v[182:185], v[120:123]
	v_mfma_f32_16x16x32_bf16 v[116:119], v[150:153], v[194:197], v[116:119]
	v_mfma_f32_16x16x32_bf16 v[112:115], v[158:161], v[194:197], v[112:115]
	v_mfma_f32_16x16x32_bf16 v[108:111], v[150:153], v[202:205], v[108:111]
	v_mfma_f32_16x16x32_bf16 v[104:107], v[158:161], v[202:205], v[104:107]
	v_mfma_f32_16x16x32_bf16 v[100:103], v[150:153], v[228:231], v[100:103]
	v_mfma_f32_16x16x32_bf16 v[96:99], v[158:161], v[228:231], v[96:99]
	v_mfma_f32_16x16x32_bf16 v[92:95], v[162:165], v[178:181], v[92:95]
	v_mfma_f32_16x16x32_bf16 v[88:91], v[170:173], v[178:181], v[88:91]
	v_mfma_f32_16x16x32_bf16 v[84:87], v[162:165], v[190:193], v[84:87]
	v_mfma_f32_16x16x32_bf16 v[80:83], v[170:173], v[190:193], v[80:83]
	v_mfma_f32_16x16x32_bf16 v[76:79], v[162:165], v[198:201], v[76:79]
	v_mfma_f32_16x16x32_bf16 v[72:75], v[170:173], v[198:201], v[72:75]
	v_mfma_f32_16x16x32_bf16 v[68:71], v[162:165], v[206:209], v[68:71]
	v_mfma_f32_16x16x32_bf16 v[64:67], v[170:173], v[206:209], v[64:67]
	v_mfma_f32_16x16x32_bf16 v[92:95], v[166:169], v[182:185], v[92:95]
	v_mfma_f32_16x16x32_bf16 v[88:91], v[174:177], v[182:185], v[88:91]
	v_mfma_f32_16x16x32_bf16 v[84:87], v[166:169], v[194:197], v[84:87]
	v_mfma_f32_16x16x32_bf16 v[80:83], v[174:177], v[194:197], v[80:83]
	v_mfma_f32_16x16x32_bf16 v[76:79], v[166:169], v[202:205], v[76:79]
	v_mfma_f32_16x16x32_bf16 v[72:75], v[174:177], v[202:205], v[72:75]
	v_mfma_f32_16x16x32_bf16 v[68:71], v[166:169], v[228:231], v[68:71]
	v_mfma_f32_16x16x32_bf16 v[64:67], v[174:177], v[228:231], v[64:67]
	s_barrier
; #define PG8_STAGE(bufoff, gbase, voff) do { _Pragma("unroll") for (int _i = 0; _i < 2; ++_i) \
;         __builtin_amdgcn_global_load_lds((const unsigned*)((const char*)(gbase) + (voff)[_i]), (PG8_LAS unsigned*)(lds + (bufoff) + ldsw + _i * 8192), 16, 0, 0); } while (0)
; #define PG8_LDA(dst, b, h) do { _Pragma("unroll") for (int m = 0; m < 4; ++m) _Pragma("unroll") for (int k = 0; k < 2; ++k) dst[m][k] = *(const PG8_LAS bf16x8*)(lds + PG8_SA(b, h) + aoff + m * 2048 + k * 1024); } while (0)
; #define PG8_LDB(dst, b, h) do { _Pragma("unroll") for (int n = 0; n < 2; ++n) _Pragma("unroll") for (int k = 0; k < 2; ++k) dst[n][k] = *(const PG8_LAS bf16x8*)(lds + PG8_SB(b, h) + boff + n * 2048 + k * 1024); } while (0)
; #define PG8_MMA(ai, bj, At, Bt) do { __builtin_amdgcn_s_setprio(1); _Pragma("unroll") for (int m = 0; m < 4; ++m) _Pragma("unroll") for (int n = 0; n < 2; ++n) _Pragma("unroll") for (int k = 0; k < 2; ++k) \
;         acc[ai][bj][m][n] = __builtin_amdgcn_mfma_f32_16x16x32_bf16(Bt[n][k], At[m][k], acc[ai][bj][m][n], 0, 0, 0); __builtin_amdgcn_s_setprio(0); } while (0)
; template <class Epi, class Sched, bool ALIGN_EPI = false, bool SP2 = false>
; __device__ __forceinline__ void gemm_phase(PG8_LAS unsigned char* lds, const Gemm g, const Sched& S, const Epi& E) {
;     ...
;             PG8_LDB(B0, 0, 0); PG8_LDB(B1, 0, 1); PG8_SCHED; PG8_LDA(At, 0, 0); PG8_STAGE(PG8_SA(1, 1), a1 + hstep, voffA);
;             PG8_WAIT_V(8); PG8_WAIT_L(0); PG8_BAR; PG8_MMA(0, 0, At, B0); PG8_MMA(0, 1, At, B1); PG8_BAR; PG8_SCHED;
;             PG8_LDA(At, 0, 1); PG8_STAGE(PG8_SB(0, 0), b2, voffB); PG8_STAGE(PG8_SB(0, 1), b2 + hstep, voffB); PG8_STAGE(PG8_SA(0, 0), a2, voffA);
;             PG8_WAIT_V(8); PG8_WAIT_L(0); PG8_BAR; PG8_MMA(1, 0, At, B0); PG8_MMA(1, 1, At, B1); PG8_BAR; PG8_SCHED;
;             PG8_LDB(B0, 1, 0); PG8_LDB(B1, 1, 1); PG8_SCHED; PG8_LDA(At, 1, 0); PG8_STAGE(PG8_SA(0, 1), a2 + hstep, voffA);
;             PG8_WAIT_V(8); PG8_WAIT_L(0); PG8_BAR; PG8_MMA(0, 0, At, B0); PG8_MMA(0, 1, At, B1); PG8_BAR; PG8_SCHED;
;             PG8_LDA(At, 1, 1); PG8_STAGE(PG8_SB(1, 0), b3, voffB); PG8_STAGE(PG8_SB(1, 1), b3 + hstep, voffB); PG8_STAGE(PG8_SA(1, 0), a3, voffA);
;             PG8_WAIT_V(8); PG8_WAIT_L(0); PG8_BAR; PG8_MMA(1, 0, At, B0); PG8_MMA(1, 1, At, B1); PG8_BAR; PG8_SCHED;
;     ...
;         if constexpr (ALIGN_EPI) { if (wr == 0) PG8_BAR; }
	s_setprio 1
	s_add_i32 s64, s84, s18
	v_lshl_add_u64 v[186:187], v[186:187], 0, s[90:91]
	s_mov_b32 m0, s64
	ds_read_b128 v[178:181], v148 offset:49152
	ds_read_b128 v[182:185], v148 offset:50176
	ds_read_b128 v[190:193], v148 offset:51200
	ds_read_b128 v[194:197], v148 offset:52224
	ds_read_b128 v[198:201], v148 offset:53248
	ds_read_b128 v[202:205], v148 offset:54272
	ds_read_b128 v[206:209], v148 offset:55296
	ds_read_b128 v[228:231], v148 offset:56320
	global_load_lds_dwordx4 v[186:187], off
	s_add_i32 m0, s64, 0x2000
	s_add_u32 s58, s58, 0x40080
	v_lshl_add_u64 v[186:187], v[188:189], 0, s[90:91]
	s_addc_u32 s59, s59, 0
	s_add_i32 s64, s85, s18
	global_load_lds_dwordx4 v[186:187], off
	v_lshl_add_u64 v[186:187], s[58:59], 0, v[128:129]
	s_mov_b32 m0, s64
	s_nop 0
	global_load_lds_dwordx4 v[186:187], off
	v_lshl_add_u64 v[186:187], s[58:59], 0, v[130:131]
	s_add_i32 m0, s64, 0x2000
	s_nop 0
	global_load_lds_dwordx4 v[186:187], off
	v_lshl_add_u64 v[186:187], v[210:211], 0, s[90:91]
	s_mov_b32 m0, s28
	s_nop 0
	global_load_lds_dwordx4 v[186:187], off
	v_lshl_add_u64 v[186:187], v[232:233], 0, s[90:91]
	s_mov_b32 m0, s29
	s_nop 0
	global_load_lds_dwordx4 v[186:187], off
	s_waitcnt vmcnt(8)
	s_waitcnt lgkmcnt(0)
	s_barrier
	s_setprio 0
	s_waitcnt lgkmcnt(0)
	v_mfma_f32_16x16x32_bf16 v[60:63], v[142:145], v[178:181], v[60:63]
	v_mfma_f32_16x16x32_bf16 v[56:59], v[154:157], v[178:181], v[56:59]
	v_mfma_f32_16x16x32_bf16 v[52:55], v[142:145], v[190:193], v[52:55]
	v_mfma_f32_16x16x32_bf16 v[48:51], v[154:157], v[190:193], v[48:51]
	v_mfma_f32_16x16x32_bf16 v[44:47], v[142:145], v[198:201], v[44:47]
	v_mfma_f32_16x16x32_bf16 v[40:43], v[154:157], v[198:201], v[40:43]
	v_mfma_f32_16x16x32_bf16 v[36:39], v[142:145], v[206:209], v[36:39]
	v_mfma_f32_16x16x32_bf16 v[32:35], v[154:157], v[206:209], v[32:35]
	v_mfma_f32_16x16x32_bf16 v[60:63], v[150:153], v[182:185], v[60:63]
	v_mfma_f32_16x16x32_bf16 v[56:59], v[158:161], v[182:185], v[56:59]
	v_mfma_f32_16x16x32_bf16 v[52:55], v[150:153], v[194:197], v[52:55]
	v_mfma_f32_16x16x32_bf16 v[48:51], v[158:161], v[194:197], v[48:51]
	v_mfma_f32_16x16x32_bf16 v[44:47], v[150:153], v[202:205], v[44:47]
	v_mfma_f32_16x16x32_bf16 v[40:43], v[158:161], v[202:205], v[40:43]
	v_mfma_f32_16x16x32_bf16 v[36:39], v[150:153], v[228:231], v[36:39]
	v_mfma_f32_16x16x32_bf16 v[32:35], v[158:161], v[228:231], v[32:35]
	v_mfma_f32_16x16x32_bf16 v[28:31], v[162:165], v[178:181], v[28:31]
	v_mfma_f32_16x16x32_bf16 v[24:27], v[170:173], v[178:181], v[24:27]
	v_mfma_f32_16x16x32_bf16 v[20:23], v[162:165], v[190:193], v[20:23]
	v_mfma_f32_16x16x32_bf16 v[16:19], v[170:173], v[190:193], v[16:19]
	v_mfma_f32_16x16x32_bf16 v[12:15], v[162:165], v[198:201], v[12:15]
	v_mfma_f32_16x16x32_bf16 v[8:11], v[170:173], v[198:201], v[8:11]
	v_mfma_f32_16x16x32_bf16 v[4:7], v[162:165], v[206:209], v[4:7]
	v_mfma_f32_16x16x32_bf16 v[0:3], v[170:173], v[206:209], v[0:3]
	v_mfma_f32_16x16x32_bf16 v[28:31], v[166:169], v[182:185], v[28:31]
	v_mfma_f32_16x16x32_bf16 v[24:27], v[174:177], v[182:185], v[24:27]
	v_mfma_f32_16x16x32_bf16 v[20:23], v[166:169], v[194:197], v[20:23]
	v_mfma_f32_16x16x32_bf16 v[16:19], v[174:177], v[194:197], v[16:19]
	v_mfma_f32_16x16x32_bf16 v[12:15], v[166:169], v[202:205], v[12:15]
	v_mfma_f32_16x16x32_bf16 v[8:11], v[174:177], v[202:205], v[8:11]
	v_mfma_f32_16x16x32_bf16 v[4:7], v[166:169], v[228:231], v[4:7]
	v_mfma_f32_16x16x32_bf16 v[0:3], v[174:177], v[228:231], v[0:3]
	s_barrier
	s_setprio 1
	s_add_i32 s94, s94, 2
	s_add_u32 s72, s72, 0x100
	s_addc_u32 s73, s73, 0
	s_add_u32 s92, s92, 0x100
	s_addc_u32 s93, s93, 0
	s_cmp_gt_u32 s94, 13
	s_cbranch_scc0 .LBB0_164
	s_setprio 0
	s_and_b64 vcc, exec, s[48:49]
	s_cbranch_vccz .LBB0_167
	s_barrier

; #define PG8_STAGE(bufoff, gbase, voff) do { _Pragma("unroll") for (int _i = 0; _i < 2; ++_i) \
;         __builtin_amdgcn_global_load_lds((const unsigned*)((const char*)(gbase) + (voff)[_i]), (PG8_LAS unsigned*)(lds + (bufoff) + ldsw + _i * 8192), 16, 0, 0); } while (0)
; #define PG8_LDA(dst, b, h) do { _Pragma("unroll") for (int m = 0; m < 4; ++m) _Pragma("unroll") for (int k = 0; k < 2; ++k) dst[m][k] = *(const PG8_LAS bf16x8*)(lds + PG8_SA(b, h) + aoff + m * 2048 + k * 1024); } while (0)
; #define PG8_LDB(dst, b, h) do { _Pragma("unroll") for (int n = 0; n < 2; ++n) _Pragma("unroll") for (int k = 0; k < 2; ++k) dst[n][k] = *(const PG8_LAS bf16x8*)(lds + PG8_SB(b, h) + boff + n * 2048 + k * 1024); } while (0)
; #define PG8_MMA(ai, bj, At, Bt) do { __builtin_amdgcn_s_setprio(1); _Pragma("unroll") for (int m = 0; m < 4; ++m) _Pragma("unroll") for (int n = 0; n < 2; ++n) _Pragma("unroll") for (int k = 0; k < 2; ++k) \
;         acc[ai][bj][m][n] = __builtin_amdgcn_mfma_f32_16x16x32_bf16(Bt[n][k], At[m][k], acc[ai][bj][m][n], 0, 0, 0); __builtin_amdgcn_s_setprio(0); } while (0)
; #define PG8_WAIT_V(n) asm volatile("s_waitcnt vmcnt(" #n ")" ::: "memory")
; #define PG8_WAIT_L(n) asm volatile("s_waitcnt lgkmcnt(" #n ")" ::: "memory")
; #define PG8_BAR __builtin_amdgcn_s_barrier()
; #define PG8_SCHED __builtin_amdgcn_sched_barrier(0)
; template <class Epi, class Sched, bool ALIGN_EPI = false, bool SP2 = false>
; __device__ __forceinline__ void gemm_phase(PG8_LAS unsigned char* lds, const Gemm g, const Sched& S, const Epi& E) {
;     ...
;             const bool last = (t == nt - 2);
;             const char* a1 = cA + (size_t)(t + 1) * kstep;
;             const char* a2 = last ? nA : cA + (size_t)(t + 2) * kstep; const char* b2 = last ? nB : cB + (size_t)(t + 2) * kstep;
;             const char* a3 = a2 + kstep; const char* b3 = b2 + kstep;
;             if (last && has_next) S.a_ready(nxt);
;             if constexpr (SP2) {
;             PG8_LDB(B0, 0, 0); PG8_LDB(B1, 0, 1); PG8_SCHED; PG8_LDA(At, 0, 0); PG8_STAGE(PG8_SA(1, 1), a1 + hstep, voffA);
;             PG8_WAIT_V(8); PG8_WAIT_L(0); PG8_BAR; PG8_MMA(0, 0, At, B0); PG8_MMA(0, 1, At, B1); PG8_BAR; PG8_SCHED;
.LBB0_564:
	s_add_u32 s44, vcc_lo, 0xfffc0080
	s_addc_u32 s45, vcc_hi, -1
	s_add_i32 s85, 0, 0x10000
	s_cmp_eq_u32 s84, 12
	s_cselect_b32 s93, s36, s45
	s_cselect_b32 s92, s37, s44
	s_cselect_b32 s59, s67, s94
	s_cselect_b32 s58, s73, s88
	s_add_i32 s8, 0, 0x14000
	v_add_u32_e32 v142, s85, v201
	v_add_u32_e32 v168, s8, v201
	ds_read_b128 v[130:133], v142
	ds_read_b128 v[134:137], v142 offset:1024
	ds_read_b128 v[138:141], v142 offset:2048
	ds_read_b128 v[142:145], v142 offset:3072
	ds_read_b128 v[156:159], v168
	ds_read_b128 v[160:163], v168 offset:1024
	ds_read_b128 v[164:167], v168 offset:2048
	ds_read_b128 v[168:171], v168 offset:3072
	v_lshl_add_u64 v[208:209], vcc, 0, v[152:153]
	s_add_i32 m0, s15, 0xc000
	ds_read_b128 v[172:175], v203
	ds_read_b128 v[176:179], v203 offset:1024
	ds_read_b128 v[180:183], v203 offset:2048
	ds_read_b128 v[184:187], v203 offset:3072
	ds_read_b128 v[188:191], v203 offset:4096
	ds_read_b128 v[192:195], v203 offset:5120
	ds_read_b128 v[196:199], v203 offset:6144
	ds_read_b128 v[204:207], v203 offset:7168
	global_load_lds_dwordx4 v[208:209], off
	v_lshl_add_u64 v[208:209], vcc, 0, v[154:155]
	s_add_i32 m0, s15, 0xe000
	s_nop 0
	global_load_lds_dwordx4 v[208:209], off
	s_waitcnt vmcnt(8)
	s_waitcnt lgkmcnt(0)
	s_barrier
	s_setprio 0
	s_waitcnt lgkmcnt(0)
	v_mfma_f32_16x16x32_bf16 v[124:127], v[130:133], v[172:175], v[124:127]
	v_mfma_f32_16x16x32_bf16 v[120:123], v[138:141], v[172:175], v[120:123]
	v_mfma_f32_16x16x32_bf16 v[108:111], v[130:133], v[180:183], v[108:111]
	v_mfma_f32_16x16x32_bf16 v[104:107], v[138:141], v[180:183], v[104:107]
	v_mfma_f32_16x16x32_bf16 v[92:95], v[130:133], v[188:191], v[92:95]
	v_mfma_f32_16x16x32_bf16 v[88:91], v[138:141], v[188:191], v[88:91]
	v_mfma_f32_16x16x32_bf16 v[76:79], v[130:133], v[196:199], v[76:79]
	v_mfma_f32_16x16x32_bf16 v[72:75], v[138:141], v[196:199], v[72:75]
	v_mfma_f32_16x16x32_bf16 v[124:127], v[134:137], v[176:179], v[124:127]
	v_mfma_f32_16x16x32_bf16 v[120:123], v[142:145], v[176:179], v[120:123]
	v_mfma_f32_16x16x32_bf16 v[108:111], v[134:137], v[184:187], v[108:111]
	v_mfma_f32_16x16x32_bf16 v[104:107], v[142:145], v[184:187], v[104:107]
	v_mfma_f32_16x16x32_bf16 v[92:95], v[134:137], v[192:195], v[92:95]
	v_mfma_f32_16x16x32_bf16 v[88:91], v[142:145], v[192:195], v[88:91]
	v_mfma_f32_16x16x32_bf16 v[76:79], v[134:137], v[204:207], v[76:79]
	v_mfma_f32_16x16x32_bf16 v[72:75], v[142:145], v[204:207], v[72:75]
	v_mfma_f32_16x16x32_bf16 v[116:119], v[156:159], v[172:175], v[116:119]
	v_mfma_f32_16x16x32_bf16 v[112:115], v[164:167], v[172:175], v[112:115]
	v_mfma_f32_16x16x32_bf16 v[100:103], v[156:159], v[180:183], v[100:103]
	v_mfma_f32_16x16x32_bf16 v[96:99], v[164:167], v[180:183], v[96:99]
	v_mfma_f32_16x16x32_bf16 v[84:87], v[156:159], v[188:191], v[84:87]
	v_mfma_f32_16x16x32_bf16 v[80:83], v[164:167], v[188:191], v[80:83]
	v_mfma_f32_16x16x32_bf16 v[68:71], v[156:159], v[196:199], v[68:71]
	v_mfma_f32_16x16x32_bf16 v[64:67], v[164:167], v[196:199], v[64:67]
	v_mfma_f32_16x16x32_bf16 v[116:119], v[160:163], v[176:179], v[116:119]
	v_mfma_f32_16x16x32_bf16 v[112:115], v[168:171], v[176:179], v[112:115]
	v_mfma_f32_16x16x32_bf16 v[100:103], v[160:163], v[184:187], v[100:103]
	v_mfma_f32_16x16x32_bf16 v[96:99], v[168:171], v[184:187], v[96:99]
	v_mfma_f32_16x16x32_bf16 v[84:87], v[160:163], v[192:195], v[84:87]
	v_mfma_f32_16x16x32_bf16 v[80:83], v[168:171], v[192:195], v[80:83]
	v_mfma_f32_16x16x32_bf16 v[68:71], v[160:163], v[204:207], v[68:71]
	v_mfma_f32_16x16x32_bf16 v[64:67], v[168:171], v[204:207], v[64:67]
	s_barrier
	s_setprio 1
	s_add_i32 s44, s85, s14
	v_lshl_add_u64 v[208:209], s[58:59], 0, v[128:129]
	s_mov_b32 m0, s44
	ds_read_b128 v[172:175], v203 offset:16384
	ds_read_b128 v[176:179], v203 offset:17408
	ds_read_b128 v[180:183], v203 offset:18432
	ds_read_b128 v[184:187], v203 offset:19456
	ds_read_b128 v[188:191], v203 offset:20480
	ds_read_b128 v[192:195], v203 offset:21504
	ds_read_b128 v[196:199], v203 offset:22528
	ds_read_b128 v[204:207], v203 offset:23552
	global_load_lds_dwordx4 v[208:209], off
	s_add_i32 m0, s44, 0x2000
	s_add_u32 s44, s58, 0x40000
	v_lshl_add_u64 v[210:211], s[58:59], 0, v[146:147]
	s_addc_u32 s45, s59, 0
	s_add_i32 s8, s8, s14
	global_load_lds_dwordx4 v[210:211], off
	v_lshl_add_u64 v[214:215], s[44:45], 0, v[128:129]
	s_mov_b32 m0, s8
	v_lshl_add_u64 v[222:223], s[92:93], 0, v[148:149]
	global_load_lds_dwordx4 v[214:215], off
	v_lshl_add_u64 v[214:215], s[44:45], 0, v[146:147]
	s_add_i32 m0, s8, 0x2000
	s_nop 0
	global_load_lds_dwordx4 v[214:215], off
	v_lshl_add_u64 v[214:215], s[92:93], 0, v[150:151]
	s_mov_b32 m0, s15
	s_nop 0
	global_load_lds_dwordx4 v[214:215], off
	s_mov_b32 m0, s17
	s_nop 0
	global_load_lds_dwordx4 v[222:223], off
	s_waitcnt vmcnt(8)
	s_waitcnt lgkmcnt(0)
	s_barrier
; #define PG8_STAGE(bufoff, gbase, voff) do { _Pragma("unroll") for (int _i = 0; _i < 2; ++_i) \
;         __builtin_amdgcn_global_load_lds((const unsigned*)((const char*)(gbase) + (voff)[_i]), (PG8_LAS unsigned*)(lds + (bufoff) + ldsw + _i * 8192), 16, 0, 0); } while (0)
; #define PG8_LDA(dst, b, h) do { _Pragma("unroll") for (int m = 0; m < 4; ++m) _Pragma("unroll") for (int k = 0; k < 2; ++k) dst[m][k] = *(const PG8_LAS bf16x8*)(lds + PG8_SA(b, h) + aoff + m * 2048 + k * 1024); } while (0)
; #define PG8_LDB(dst, b, h) do { _Pragma("unroll") for (int n = 0; n < 2; ++n) _Pragma("unroll") for (int k = 0; k < 2; ++k) dst[n][k] = *(const PG8_LAS bf16x8*)(lds + PG8_SB(b, h) + boff + n * 2048 + k * 1024); } while (0)
; #define PG8_MMA(ai, bj, At, Bt) do { __builtin_amdgcn_s_setprio(1); _Pragma("unroll") for (int m = 0; m < 4; ++m) _Pragma("unroll") for (int n = 0; n < 2; ++n) _Pragma("unroll") for (int k = 0; k < 2; ++k) \
;         acc[ai][bj][m][n] = __builtin_amdgcn_mfma_f32_16x16x32_bf16(Bt[n][k], At[m][k], acc[ai][bj][m][n], 0, 0, 0); __builtin_amdgcn_s_setprio(0); } while (0)
; #define PG8_WAIT_V(n) asm volatile("s_waitcnt vmcnt(" #n ")" ::: "memory")
; template <class Epi, class Sched, bool ALIGN_EPI = false, bool SP2 = false>
; __device__ __forceinline__ void gemm_phase(PG8_LAS unsigned char* lds, const Gemm g, const Sched& S, const Epi& E) {
;     ...
;             PG8_LDB(B0, 0, 0); PG8_LDB(B1, 0, 1); PG8_SCHED; PG8_LDA(At, 0, 0); PG8_STAGE(PG8_SA(1, 1), a1 + hstep, voffA);
;             PG8_WAIT_V(8); PG8_WAIT_L(0); PG8_BAR; PG8_MMA(0, 0, At, B0); PG8_MMA(0, 1, At, B1); PG8_BAR; PG8_SCHED;
;             PG8_LDA(At, 0, 1); PG8_STAGE(PG8_SB(0, 0), b2, voffB); PG8_STAGE(PG8_SB(0, 1), b2 + hstep, voffB); PG8_STAGE(PG8_SA(0, 0), a2, voffA);
;             PG8_WAIT_V(8); PG8_WAIT_L(0); PG8_BAR; PG8_MMA(1, 0, At, B0); PG8_MMA(1, 1, At, B1); PG8_BAR; PG8_SCHED;
;             PG8_LDB(B0, 1, 0); PG8_LDB(B1, 1, 1); PG8_SCHED; PG8_LDA(At, 1, 0); PG8_STAGE(PG8_SA(0, 1), a2 + hstep, voffA);
;             PG8_WAIT_V(8); PG8_WAIT_L(0); PG8_BAR; PG8_MMA(0, 0, At, B0); PG8_MMA(0, 1, At, B1); PG8_BAR; PG8_SCHED;
;             PG8_LDA(At, 1, 1); PG8_STAGE(PG8_SB(1, 0), b3, voffB); PG8_STAGE(PG8_SB(1, 1), b3 + hstep, voffB); PG8_STAGE(PG8_SA(1, 0), a3, voffA);
;             PG8_WAIT_V(8); PG8_WAIT_L(0); PG8_BAR; PG8_MMA(1, 0, At, B0); PG8_MMA(1, 1, At, B1); PG8_BAR; PG8_SCHED;
	s_setprio 0
	s_waitcnt lgkmcnt(0)
	v_mfma_f32_16x16x32_bf16 v[60:63], v[130:133], v[172:175], v[60:63]
	v_mfma_f32_16x16x32_bf16 v[56:59], v[138:141], v[172:175], v[56:59]
	v_mfma_f32_16x16x32_bf16 v[44:47], v[130:133], v[180:183], v[44:47]
	v_mfma_f32_16x16x32_bf16 v[40:43], v[138:141], v[180:183], v[40:43]
	v_mfma_f32_16x16x32_bf16 v[28:31], v[130:133], v[188:191], v[28:31]
	v_mfma_f32_16x16x32_bf16 v[24:27], v[138:141], v[188:191], v[24:27]
	v_mfma_f32_16x16x32_bf16 v[12:15], v[130:133], v[196:199], v[12:15]
	v_mfma_f32_16x16x32_bf16 v[8:11], v[138:141], v[196:199], v[8:11]
	v_mfma_f32_16x16x32_bf16 v[60:63], v[134:137], v[176:179], v[60:63]
	v_mfma_f32_16x16x32_bf16 v[56:59], v[142:145], v[176:179], v[56:59]
	v_mfma_f32_16x16x32_bf16 v[44:47], v[134:137], v[184:187], v[44:47]
	v_mfma_f32_16x16x32_bf16 v[40:43], v[142:145], v[184:187], v[40:43]
	v_mfma_f32_16x16x32_bf16 v[28:31], v[134:137], v[192:195], v[28:31]
	v_mfma_f32_16x16x32_bf16 v[24:27], v[142:145], v[192:195], v[24:27]
	v_mfma_f32_16x16x32_bf16 v[12:15], v[134:137], v[204:207], v[12:15]
	v_mfma_f32_16x16x32_bf16 v[8:11], v[142:145], v[204:207], v[8:11]
	v_mfma_f32_16x16x32_bf16 v[52:55], v[156:159], v[172:175], v[52:55]
	v_mfma_f32_16x16x32_bf16 v[48:51], v[164:167], v[172:175], v[48:51]
	v_mfma_f32_16x16x32_bf16 v[36:39], v[156:159], v[180:183], v[36:39]
	v_mfma_f32_16x16x32_bf16 v[32:35], v[164:167], v[180:183], v[32:35]
	v_mfma_f32_16x16x32_bf16 v[20:23], v[156:159], v[188:191], v[20:23]
	v_mfma_f32_16x16x32_bf16 v[16:19], v[164:167], v[188:191], v[16:19]
	v_mfma_f32_16x16x32_bf16 v[4:7], v[156:159], v[196:199], v[4:7]
	v_mfma_f32_16x16x32_bf16 v[0:3], v[164:167], v[196:199], v[0:3]
	v_mfma_f32_16x16x32_bf16 v[52:55], v[160:163], v[176:179], v[52:55]
	v_mfma_f32_16x16x32_bf16 v[48:51], v[168:171], v[176:179], v[48:51]
	v_mfma_f32_16x16x32_bf16 v[36:39], v[160:163], v[184:187], v[36:39]
	v_mfma_f32_16x16x32_bf16 v[32:35], v[168:171], v[184:187], v[32:35]
	v_mfma_f32_16x16x32_bf16 v[20:23], v[160:163], v[192:195], v[20:23]
	v_mfma_f32_16x16x32_bf16 v[16:19], v[168:171], v[192:195], v[16:19]
	v_mfma_f32_16x16x32_bf16 v[4:7], v[160:163], v[204:207], v[4:7]
	v_mfma_f32_16x16x32_bf16 v[0:3], v[168:171], v[204:207], v[0:3]
	s_barrier
	s_setprio 1
	s_add_i32 s8, 0, 0x18000
	s_add_i32 s85, 0, 0x1c000
	v_add_u32_e32 v142, s8, v201
	v_add_u32_e32 v168, s85, v201
	ds_read_b128 v[130:133], v142
	ds_read_b128 v[134:137], v142 offset:1024
	ds_read_b128 v[138:141], v142 offset:2048
	ds_read_b128 v[142:145], v142 offset:3072
	ds_read_b128 v[156:159], v168
	ds_read_b128 v[160:163], v168 offset:1024
	ds_read_b128 v[164:167], v168 offset:2048
	ds_read_b128 v[168:171], v168 offset:3072
	s_add_u32 s44, s92, 0x40000
	s_addc_u32 s45, s93, 0
	s_mov_b32 m0, s18
	v_lshl_add_u64 v[228:229], s[44:45], 0, v[150:151]
	ds_read_b128 v[172:175], v203 offset:32768
	ds_read_b128 v[176:179], v203 offset:33792
	ds_read_b128 v[180:183], v203 offset:34816
	ds_read_b128 v[184:187], v203 offset:35840
	ds_read_b128 v[188:191], v203 offset:36864
	ds_read_b128 v[192:195], v203 offset:37888
	ds_read_b128 v[196:199], v203 offset:38912
	ds_read_b128 v[204:207], v203 offset:39936
	global_load_lds_dwordx4 v[228:229], off
	v_lshl_add_u64 v[228:229], s[44:45], 0, v[148:149]
	s_mov_b32 m0, s19
	s_nop 0
	global_load_lds_dwordx4 v[228:229], off
	s_waitcnt vmcnt(8)
	s_waitcnt lgkmcnt(0)
	s_barrier
	s_setprio 0
	s_waitcnt lgkmcnt(0)
	v_mfma_f32_16x16x32_bf16 v[124:127], v[130:133], v[172:175], v[124:127]
	v_mfma_f32_16x16x32_bf16 v[120:123], v[138:141], v[172:175], v[120:123]
	v_mfma_f32_16x16x32_bf16 v[108:111], v[130:133], v[180:183], v[108:111]
	v_mfma_f32_16x16x32_bf16 v[104:107], v[138:141], v[180:183], v[104:107]
	v_mfma_f32_16x16x32_bf16 v[92:95], v[130:133], v[188:191], v[92:95]
	v_mfma_f32_16x16x32_bf16 v[88:91], v[138:141], v[188:191], v[88:91]
	v_mfma_f32_16x16x32_bf16 v[76:79], v[130:133], v[196:199], v[76:79]
	v_mfma_f32_16x16x32_bf16 v[72:75], v[138:141], v[196:199], v[72:75]
	v_mfma_f32_16x16x32_bf16 v[124:127], v[134:137], v[176:179], v[124:127]
	v_mfma_f32_16x16x32_bf16 v[120:123], v[142:145], v[176:179], v[120:123]
	v_mfma_f32_16x16x32_bf16 v[108:111], v[134:137], v[184:187], v[108:111]
	v_mfma_f32_16x16x32_bf16 v[104:107], v[142:145], v[184:187], v[104:107]
	v_mfma_f32_16x16x32_bf16 v[92:95], v[134:137], v[192:195], v[92:95]
	v_mfma_f32_16x16x32_bf16 v[88:91], v[142:145], v[192:195], v[88:91]
	v_mfma_f32_16x16x32_bf16 v[76:79], v[134:137], v[204:207], v[76:79]
	v_mfma_f32_16x16x32_bf16 v[72:75], v[142:145], v[204:207], v[72:75]
	v_mfma_f32_16x16x32_bf16 v[116:119], v[156:159], v[172:175], v[116:119]
	v_mfma_f32_16x16x32_bf16 v[112:115], v[164:167], v[172:175], v[112:115]
	v_mfma_f32_16x16x32_bf16 v[100:103], v[156:159], v[180:183], v[100:103]
	v_mfma_f32_16x16x32_bf16 v[96:99], v[164:167], v[180:183], v[96:99]
	v_mfma_f32_16x16x32_bf16 v[84:87], v[156:159], v[188:191], v[84:87]
	v_mfma_f32_16x16x32_bf16 v[80:83], v[164:167], v[188:191], v[80:83]
	v_mfma_f32_16x16x32_bf16 v[68:71], v[156:159], v[196:199], v[68:71]
	v_mfma_f32_16x16x32_bf16 v[64:67], v[164:167], v[196:199], v[64:67]
	v_mfma_f32_16x16x32_bf16 v[116:119], v[160:163], v[176:179], v[116:119]
	v_mfma_f32_16x16x32_bf16 v[112:115], v[168:171], v[176:179], v[112:115]
	v_mfma_f32_16x16x32_bf16 v[100:103], v[160:163], v[184:187], v[100:103]
	v_mfma_f32_16x16x32_bf16 v[96:99], v[168:171], v[184:187], v[96:99]
	v_mfma_f32_16x16x32_bf16 v[84:87], v[160:163], v[192:195], v[84:87]
	v_mfma_f32_16x16x32_bf16 v[80:83], v[168:171], v[192:195], v[80:83]
	v_mfma_f32_16x16x32_bf16 v[68:71], v[160:163], v[204:207], v[68:71]
	v_mfma_f32_16x16x32_bf16 v[64:67], v[168:171], v[204:207], v[64:67]
	s_barrier
; #define PG8_STAGE(bufoff, gbase, voff) do { _Pragma("unroll") for (int _i = 0; _i < 2; ++_i) \
;         __builtin_amdgcn_global_load_lds((const unsigned*)((const char*)(gbase) + (voff)[_i]), (PG8_LAS unsigned*)(lds + (bufoff) + ldsw + _i * 8192), 16, 0, 0); } while (0)
; #define PG8_LDA(dst, b, h) do { _Pragma("unroll") for (int m = 0; m < 4; ++m) _Pragma("unroll") for (int k = 0; k < 2; ++k) dst[m][k] = *(const PG8_LAS bf16x8*)(lds + PG8_SA(b, h) + aoff + m * 2048 + k * 1024); } while (0)
; #define PG8_LDB(dst, b, h) do { _Pragma("unroll") for (int n = 0; n < 2; ++n) _Pragma("unroll") for (int k = 0; k < 2; ++k) dst[n][k] = *(const PG8_LAS bf16x8*)(lds + PG8_SB(b, h) + boff + n * 2048 + k * 1024); } while (0)
; #define PG8_MMA(ai, bj, At, Bt) do { __builtin_amdgcn_s_setprio(1); _Pragma("unroll") for (int m = 0; m < 4; ++m) _Pragma("unroll") for (int n = 0; n < 2; ++n) _Pragma("unroll") for (int k = 0; k < 2; ++k) \
;         acc[ai][bj][m][n] = __builtin_amdgcn_mfma_f32_16x16x32_bf16(Bt[n][k], At[m][k], acc[ai][bj][m][n], 0, 0, 0); __builtin_amdgcn_s_setprio(0); } while (0)
; template <class Epi, class Sched, bool ALIGN_EPI = false, bool SP2 = false>
; __device__ __forceinline__ void gemm_phase(PG8_LAS unsigned char* lds, const Gemm g, const Sched& S, const Epi& E) {
;     ...
;             PG8_LDB(B0, 0, 0); PG8_LDB(B1, 0, 1); PG8_SCHED; PG8_LDA(At, 0, 0); PG8_STAGE(PG8_SA(1, 1), a1 + hstep, voffA);
;             PG8_WAIT_V(8); PG8_WAIT_L(0); PG8_BAR; PG8_MMA(0, 0, At, B0); PG8_MMA(0, 1, At, B1); PG8_BAR; PG8_SCHED;
;             PG8_LDA(At, 0, 1); PG8_STAGE(PG8_SB(0, 0), b2, voffB); PG8_STAGE(PG8_SB(0, 1), b2 + hstep, voffB); PG8_STAGE(PG8_SA(0, 0), a2, voffA);
;             PG8_WAIT_V(8); PG8_WAIT_L(0); PG8_BAR; PG8_MMA(1, 0, At, B0); PG8_MMA(1, 1, At, B1); PG8_BAR; PG8_SCHED;
;             PG8_LDB(B0, 1, 0); PG8_LDB(B1, 1, 1); PG8_SCHED; PG8_LDA(At, 1, 0); PG8_STAGE(PG8_SA(0, 1), a2 + hstep, voffA);
;             PG8_WAIT_V(8); PG8_WAIT_L(0); PG8_BAR; PG8_MMA(0, 0, At, B0); PG8_MMA(0, 1, At, B1); PG8_BAR; PG8_SCHED;
;             PG8_LDA(At, 1, 1); PG8_STAGE(PG8_SB(1, 0), b3, voffB); PG8_STAGE(PG8_SB(1, 1), b3 + hstep, voffB); PG8_STAGE(PG8_SA(1, 0), a3, voffA);
;             PG8_WAIT_V(8); PG8_WAIT_L(0); PG8_BAR; PG8_MMA(1, 0, At, B0); PG8_MMA(1, 1, At, B1); PG8_BAR; PG8_SCHED;
;     ...
;         if constexpr (ALIGN_EPI) { if (wr == 0) PG8_BAR; }
	s_setprio 1
	s_add_i32 s8, s8, s14
	v_lshl_add_u64 v[208:209], v[208:209], 0, s[90:91]
	s_mov_b32 m0, s8
	ds_read_b128 v[172:175], v203 offset:49152
	ds_read_b128 v[176:179], v203 offset:50176
	ds_read_b128 v[180:183], v203 offset:51200
	ds_read_b128 v[184:187], v203 offset:52224
	ds_read_b128 v[188:191], v203 offset:53248
	ds_read_b128 v[192:195], v203 offset:54272
	ds_read_b128 v[196:199], v203 offset:55296
	ds_read_b128 v[204:207], v203 offset:56320
	global_load_lds_dwordx4 v[208:209], off
	s_add_i32 m0, s8, 0x2000
	s_add_u32 s44, s58, 0x40080
	v_lshl_add_u64 v[208:209], v[210:211], 0, s[90:91]
	s_addc_u32 s45, s59, 0
	s_add_i32 s8, s85, s14
	global_load_lds_dwordx4 v[208:209], off
	v_lshl_add_u64 v[208:209], s[44:45], 0, v[128:129]
	s_mov_b32 m0, s8
	s_nop 0
	global_load_lds_dwordx4 v[208:209], off
	v_lshl_add_u64 v[208:209], s[44:45], 0, v[146:147]
	s_add_i32 m0, s8, 0x2000
	s_nop 0
	global_load_lds_dwordx4 v[208:209], off
	v_lshl_add_u64 v[208:209], v[214:215], 0, s[90:91]
	s_mov_b32 m0, s30
	s_nop 0
	global_load_lds_dwordx4 v[208:209], off
	v_lshl_add_u64 v[208:209], v[222:223], 0, s[90:91]
	s_mov_b32 m0, s31
	s_nop 0
	global_load_lds_dwordx4 v[208:209], off
	s_waitcnt vmcnt(8)
	s_waitcnt lgkmcnt(0)
	s_barrier
	s_setprio 0
	s_waitcnt lgkmcnt(0)
	v_mfma_f32_16x16x32_bf16 v[60:63], v[130:133], v[172:175], v[60:63]
	v_mfma_f32_16x16x32_bf16 v[56:59], v[138:141], v[172:175], v[56:59]
	v_mfma_f32_16x16x32_bf16 v[44:47], v[130:133], v[180:183], v[44:47]
	v_mfma_f32_16x16x32_bf16 v[40:43], v[138:141], v[180:183], v[40:43]
	v_mfma_f32_16x16x32_bf16 v[28:31], v[130:133], v[188:191], v[28:31]
	v_mfma_f32_16x16x32_bf16 v[24:27], v[138:141], v[188:191], v[24:27]
	v_mfma_f32_16x16x32_bf16 v[12:15], v[130:133], v[196:199], v[12:15]
	v_mfma_f32_16x16x32_bf16 v[8:11], v[138:141], v[196:199], v[8:11]
	v_mfma_f32_16x16x32_bf16 v[60:63], v[134:137], v[176:179], v[60:63]
	v_mfma_f32_16x16x32_bf16 v[56:59], v[142:145], v[176:179], v[56:59]
	v_mfma_f32_16x16x32_bf16 v[44:47], v[134:137], v[184:187], v[44:47]
	v_mfma_f32_16x16x32_bf16 v[40:43], v[142:145], v[184:187], v[40:43]
	v_mfma_f32_16x16x32_bf16 v[28:31], v[134:137], v[192:195], v[28:31]
	v_mfma_f32_16x16x32_bf16 v[24:27], v[142:145], v[192:195], v[24:27]
	v_mfma_f32_16x16x32_bf16 v[12:15], v[134:137], v[204:207], v[12:15]
	v_mfma_f32_16x16x32_bf16 v[8:11], v[142:145], v[204:207], v[8:11]
	v_mfma_f32_16x16x32_bf16 v[52:55], v[156:159], v[172:175], v[52:55]
	v_mfma_f32_16x16x32_bf16 v[48:51], v[164:167], v[172:175], v[48:51]
	v_mfma_f32_16x16x32_bf16 v[36:39], v[156:159], v[180:183], v[36:39]
	v_mfma_f32_16x16x32_bf16 v[32:35], v[164:167], v[180:183], v[32:35]
	v_mfma_f32_16x16x32_bf16 v[20:23], v[156:159], v[188:191], v[20:23]
	v_mfma_f32_16x16x32_bf16 v[16:19], v[164:167], v[188:191], v[16:19]
	v_mfma_f32_16x16x32_bf16 v[4:7], v[156:159], v[196:199], v[4:7]
	v_mfma_f32_16x16x32_bf16 v[0:3], v[164:167], v[196:199], v[0:3]
	v_mfma_f32_16x16x32_bf16 v[52:55], v[160:163], v[176:179], v[52:55]
	v_mfma_f32_16x16x32_bf16 v[48:51], v[168:171], v[176:179], v[48:51]
	v_mfma_f32_16x16x32_bf16 v[36:39], v[160:163], v[184:187], v[36:39]
	v_mfma_f32_16x16x32_bf16 v[32:35], v[168:171], v[184:187], v[32:35]
	v_mfma_f32_16x16x32_bf16 v[20:23], v[160:163], v[192:195], v[20:23]
	v_mfma_f32_16x16x32_bf16 v[16:19], v[168:171], v[192:195], v[16:19]
	v_mfma_f32_16x16x32_bf16 v[4:7], v[160:163], v[204:207], v[4:7]
	v_mfma_f32_16x16x32_bf16 v[0:3], v[168:171], v[204:207], v[0:3]
	s_barrier
	s_setprio 1
	s_add_i32 s84, s84, 2
	s_add_u32 vcc_lo, vcc_lo, 0x100
	s_addc_u32 vcc_hi, vcc_hi, 0
	s_add_u32 s88, s88, 0x100
	s_addc_u32 s94, s94, 0
	s_cmp_gt_u32 s84, 13
	s_cbranch_scc0 .LBB0_564
	s_setprio 0
	s_and_b64 vcc, exec, s[62:63]
	s_cbranch_vccz .LBB0_567
	s_barrier

; #define PG8_STAGE(bufoff, gbase, voff) do { _Pragma("unroll") for (int _i = 0; _i < 2; ++_i) \
;         __builtin_amdgcn_global_load_lds((const unsigned*)((const char*)(gbase) + (voff)[_i]), (PG8_LAS unsigned*)(lds + (bufoff) + ldsw + _i * 8192), 16, 0, 0); } while (0)
; #define PG8_LDA(dst, b, h) do { _Pragma("unroll") for (int m = 0; m < 4; ++m) _Pragma("unroll") for (int k = 0; k < 2; ++k) dst[m][k] = *(const PG8_LAS bf16x8*)(lds + PG8_SA(b, h) + aoff + m * 2048 + k * 1024); } while (0)
; #define PG8_LDB(dst, b, h) do { _Pragma("unroll") for (int n = 0; n < 2; ++n) _Pragma("unroll") for (int k = 0; k < 2; ++k) dst[n][k] = *(const PG8_LAS bf16x8*)(lds + PG8_SB(b, h) + boff + n * 2048 + k * 1024); } while (0)
; #define PG8_MMA(ai, bj, At, Bt) do { __builtin_amdgcn_s_setprio(1); _Pragma("unroll") for (int m = 0; m < 4; ++m) _Pragma("unroll") for (int n = 0; n < 2; ++n) _Pragma("unroll") for (int k = 0; k < 2; ++k) \
;         acc[ai][bj][m][n] = __builtin_amdgcn_mfma_f32_16x16x32_bf16(Bt[n][k], At[m][k], acc[ai][bj][m][n], 0, 0, 0); __builtin_amdgcn_s_setprio(0); } while (0)
; #define PG8_WAIT_V(n) asm volatile("s_waitcnt vmcnt(" #n ")" ::: "memory")
; #define PG8_WAIT_L(n) asm volatile("s_waitcnt lgkmcnt(" #n ")" ::: "memory")
; #define PG8_BAR __builtin_amdgcn_s_barrier()
; #define PG8_SCHED __builtin_amdgcn_sched_barrier(0)
; template <class Epi, class Sched, bool ALIGN_EPI = false, bool SP2 = false>
; __device__ __forceinline__ void gemm_phase(PG8_LAS unsigned char* lds, const Gemm g, const Sched& S, const Epi& E) {
;     ...
;             const bool last = (t == nt - 2);
;             const char* a1 = cA + (size_t)(t + 1) * kstep;
;             const char* a2 = last ? nA : cA + (size_t)(t + 2) * kstep; const char* b2 = last ? nB : cB + (size_t)(t + 2) * kstep;
;             const char* a3 = a2 + kstep; const char* b3 = b2 + kstep;
;             if (last && has_next) S.a_ready(nxt);
;             if constexpr (SP2) {
;             PG8_LDB(B0, 0, 0); PG8_LDB(B1, 0, 1); PG8_SCHED; PG8_LDA(At, 0, 0); PG8_STAGE(PG8_SA(1, 1), a1 + hstep, voffA);
;             PG8_WAIT_V(8); PG8_WAIT_L(0); PG8_BAR; PG8_MMA(0, 0, At, B0); PG8_MMA(0, 1, At, B1); PG8_BAR; PG8_SCHED;
.LBB0_598:
	s_add_u32 s58, vcc_lo, 0xfffc0080
	s_addc_u32 s59, vcc_hi, -1
	s_add_i32 s84, 0, 0x10000
	s_cmp_eq_u32 s94, 12
	s_cselect_b32 s65, s35, s59
	s_cselect_b32 s64, s36, s58
	s_cselect_b32 s59, s37, s93
	s_cselect_b32 s58, s43, s88
	s_add_i32 s97, 0, 0x14000
	v_add_u32_e32 v76, s84, v228
	v_add_u32_e32 v168, s97, v228
	ds_read_b128 v[64:67], v76
	ds_read_b128 v[68:71], v76 offset:1024
	ds_read_b128 v[72:75], v76 offset:2048
	ds_read_b128 v[76:79], v76 offset:3072
	ds_read_b128 v[156:159], v168
	ds_read_b128 v[160:163], v168 offset:1024
	ds_read_b128 v[164:167], v168 offset:2048
	ds_read_b128 v[168:171], v168 offset:3072
	v_lshl_add_u64 v[204:205], vcc, 0, v[152:153]
	s_add_i32 m0, s18, 0xc000
	ds_read_b128 v[172:175], v230
	ds_read_b128 v[176:179], v230 offset:1024
	ds_read_b128 v[180:183], v230 offset:2048
	ds_read_b128 v[184:187], v230 offset:3072
	ds_read_b128 v[188:191], v230 offset:4096
	ds_read_b128 v[192:195], v230 offset:5120
	ds_read_b128 v[196:199], v230 offset:6144
	ds_read_b128 v[200:203], v230 offset:7168
	global_load_lds_dwordx4 v[204:205], off
	v_lshl_add_u64 v[204:205], vcc, 0, v[154:155]
	s_add_i32 m0, s18, 0xe000
	s_nop 0
	global_load_lds_dwordx4 v[204:205], off
	s_waitcnt vmcnt(8)
	s_waitcnt lgkmcnt(0)
	s_barrier
	s_setprio 0
	s_waitcnt lgkmcnt(0)
	v_mfma_f32_16x16x32_bf16 v[142:145], v[64:67], v[172:175], v[142:145]
	v_mfma_f32_16x16x32_bf16 v[138:141], v[72:75], v[172:175], v[138:141]
	v_mfma_f32_16x16x32_bf16 v[134:137], v[64:67], v[180:183], v[134:137]
	v_mfma_f32_16x16x32_bf16 v[124:127], v[72:75], v[180:183], v[124:127]
	v_mfma_f32_16x16x32_bf16 v[108:111], v[64:67], v[188:191], v[108:111]
	v_mfma_f32_16x16x32_bf16 v[104:107], v[72:75], v[188:191], v[104:107]
	v_mfma_f32_16x16x32_bf16 v[100:103], v[64:67], v[196:199], v[100:103]
	v_mfma_f32_16x16x32_bf16 v[92:95], v[72:75], v[196:199], v[92:95]
	v_mfma_f32_16x16x32_bf16 v[142:145], v[68:71], v[176:179], v[142:145]
	v_mfma_f32_16x16x32_bf16 v[138:141], v[76:79], v[176:179], v[138:141]
	v_mfma_f32_16x16x32_bf16 v[134:137], v[68:71], v[184:187], v[134:137]
	v_mfma_f32_16x16x32_bf16 v[124:127], v[76:79], v[184:187], v[124:127]
	v_mfma_f32_16x16x32_bf16 v[108:111], v[68:71], v[192:195], v[108:111]
	v_mfma_f32_16x16x32_bf16 v[104:107], v[76:79], v[192:195], v[104:107]
	v_mfma_f32_16x16x32_bf16 v[100:103], v[68:71], v[200:203], v[100:103]
	v_mfma_f32_16x16x32_bf16 v[92:95], v[76:79], v[200:203], v[92:95]
	v_mfma_f32_16x16x32_bf16 v[130:133], v[156:159], v[172:175], v[130:133]
	v_mfma_f32_16x16x32_bf16 v[120:123], v[164:167], v[172:175], v[120:123]
	v_mfma_f32_16x16x32_bf16 v[116:119], v[156:159], v[180:183], v[116:119]
	v_mfma_f32_16x16x32_bf16 v[112:115], v[164:167], v[180:183], v[112:115]
	v_mfma_f32_16x16x32_bf16 v[96:99], v[156:159], v[188:191], v[96:99]
	v_mfma_f32_16x16x32_bf16 v[88:91], v[164:167], v[188:191], v[88:91]
	v_mfma_f32_16x16x32_bf16 v[84:87], v[156:159], v[196:199], v[84:87]
	v_mfma_f32_16x16x32_bf16 v[80:83], v[164:167], v[196:199], v[80:83]
	v_mfma_f32_16x16x32_bf16 v[130:133], v[160:163], v[176:179], v[130:133]
	v_mfma_f32_16x16x32_bf16 v[120:123], v[168:171], v[176:179], v[120:123]
	v_mfma_f32_16x16x32_bf16 v[116:119], v[160:163], v[184:187], v[116:119]
	v_mfma_f32_16x16x32_bf16 v[112:115], v[168:171], v[184:187], v[112:115]
	v_mfma_f32_16x16x32_bf16 v[96:99], v[160:163], v[192:195], v[96:99]
	v_mfma_f32_16x16x32_bf16 v[88:91], v[168:171], v[192:195], v[88:91]
	v_mfma_f32_16x16x32_bf16 v[84:87], v[160:163], v[200:203], v[84:87]
	v_mfma_f32_16x16x32_bf16 v[80:83], v[168:171], v[200:203], v[80:83]
	s_barrier
	s_setprio 1
	s_add_i32 s84, s84, s17
	v_lshl_add_u64 v[204:205], s[58:59], 0, v[128:129]
	s_mov_b32 m0, s84
	ds_read_b128 v[172:175], v230 offset:16384
	ds_read_b128 v[176:179], v230 offset:17408
	ds_read_b128 v[180:183], v230 offset:18432
	ds_read_b128 v[184:187], v230 offset:19456
	ds_read_b128 v[188:191], v230 offset:20480
	ds_read_b128 v[192:195], v230 offset:21504
	ds_read_b128 v[196:199], v230 offset:22528
	ds_read_b128 v[200:203], v230 offset:23552
	global_load_lds_dwordx4 v[204:205], off
	s_add_i32 m0, s84, 0x2000
	s_add_u32 s84, s58, 0x40000
	v_lshl_add_u64 v[206:207], s[58:59], 0, v[146:147]
	s_addc_u32 s85, s59, 0
	s_add_i32 s97, s97, s17
	global_load_lds_dwordx4 v[206:207], off
	v_lshl_add_u64 v[208:209], s[84:85], 0, v[128:129]
	s_mov_b32 m0, s97
	v_lshl_add_u64 v[210:211], s[64:65], 0, v[148:149]
	global_load_lds_dwordx4 v[208:209], off
	v_lshl_add_u64 v[208:209], s[84:85], 0, v[146:147]
	s_add_i32 m0, s97, 0x2000
	s_nop 0
	global_load_lds_dwordx4 v[208:209], off
	v_lshl_add_u64 v[208:209], s[64:65], 0, v[150:151]
	s_mov_b32 m0, s18
	s_nop 0
	global_load_lds_dwordx4 v[208:209], off
	s_mov_b32 m0, s19
	s_nop 0
	global_load_lds_dwordx4 v[210:211], off
	s_waitcnt vmcnt(8)
	s_waitcnt lgkmcnt(0)
	s_barrier
; #define PG8_STAGE(bufoff, gbase, voff) do { _Pragma("unroll") for (int _i = 0; _i < 2; ++_i) \
;         __builtin_amdgcn_global_load_lds((const unsigned*)((const char*)(gbase) + (voff)[_i]), (PG8_LAS unsigned*)(lds + (bufoff) + ldsw + _i * 8192), 16, 0, 0); } while (0)
; #define PG8_LDA(dst, b, h) do { _Pragma("unroll") for (int m = 0; m < 4; ++m) _Pragma("unroll") for (int k = 0; k < 2; ++k) dst[m][k] = *(const PG8_LAS bf16x8*)(lds + PG8_SA(b, h) + aoff + m * 2048 + k * 1024); } while (0)
; #define PG8_LDB(dst, b, h) do { _Pragma("unroll") for (int n = 0; n < 2; ++n) _Pragma("unroll") for (int k = 0; k < 2; ++k) dst[n][k] = *(const PG8_LAS bf16x8*)(lds + PG8_SB(b, h) + boff + n * 2048 + k * 1024); } while (0)
; #define PG8_MMA(ai, bj, At, Bt) do { __builtin_amdgcn_s_setprio(1); _Pragma("unroll") for (int m = 0; m < 4; ++m) _Pragma("unroll") for (int n = 0; n < 2; ++n) _Pragma("unroll") for (int k = 0; k < 2; ++k) \
;         acc[ai][bj][m][n] = __builtin_amdgcn_mfma_f32_16x16x32_bf16(Bt[n][k], At[m][k], acc[ai][bj][m][n], 0, 0, 0); __builtin_amdgcn_s_setprio(0); } while (0)
; #define PG8_WAIT_V(n) asm volatile("s_waitcnt vmcnt(" #n ")" ::: "memory")
; template <class Epi, class Sched, bool ALIGN_EPI = false, bool SP2 = false>
; __device__ __forceinline__ void gemm_phase(PG8_LAS unsigned char* lds, const Gemm g, const Sched& S, const Epi& E) {
;     ...
;             PG8_LDB(B0, 0, 0); PG8_LDB(B1, 0, 1); PG8_SCHED; PG8_LDA(At, 0, 0); PG8_STAGE(PG8_SA(1, 1), a1 + hstep, voffA);
;             PG8_WAIT_V(8); PG8_WAIT_L(0); PG8_BAR; PG8_MMA(0, 0, At, B0); PG8_MMA(0, 1, At, B1); PG8_BAR; PG8_SCHED;
;             PG8_LDA(At, 0, 1); PG8_STAGE(PG8_SB(0, 0), b2, voffB); PG8_STAGE(PG8_SB(0, 1), b2 + hstep, voffB); PG8_STAGE(PG8_SA(0, 0), a2, voffA);
;             PG8_WAIT_V(8); PG8_WAIT_L(0); PG8_BAR; PG8_MMA(1, 0, At, B0); PG8_MMA(1, 1, At, B1); PG8_BAR; PG8_SCHED;
;             PG8_LDB(B0, 1, 0); PG8_LDB(B1, 1, 1); PG8_SCHED; PG8_LDA(At, 1, 0); PG8_STAGE(PG8_SA(0, 1), a2 + hstep, voffA);
;             PG8_WAIT_V(8); PG8_WAIT_L(0); PG8_BAR; PG8_MMA(0, 0, At, B0); PG8_MMA(0, 1, At, B1); PG8_BAR; PG8_SCHED;
;             PG8_LDA(At, 1, 1); PG8_STAGE(PG8_SB(1, 0), b3, voffB); PG8_STAGE(PG8_SB(1, 1), b3 + hstep, voffB); PG8_STAGE(PG8_SA(1, 0), a3, voffA);
;             PG8_WAIT_V(8); PG8_WAIT_L(0); PG8_BAR; PG8_MMA(1, 0, At, B0); PG8_MMA(1, 1, At, B1); PG8_BAR; PG8_SCHED;
	s_setprio 0
	s_waitcnt lgkmcnt(0)
	v_mfma_f32_16x16x32_bf16 v[60:63], v[64:67], v[172:175], v[60:63]
	v_mfma_f32_16x16x32_bf16 v[56:59], v[72:75], v[172:175], v[56:59]
	v_mfma_f32_16x16x32_bf16 v[52:55], v[64:67], v[180:183], v[52:55]
	v_mfma_f32_16x16x32_bf16 v[44:47], v[72:75], v[180:183], v[44:47]
	v_mfma_f32_16x16x32_bf16 v[28:31], v[64:67], v[188:191], v[28:31]
	v_mfma_f32_16x16x32_bf16 v[24:27], v[72:75], v[188:191], v[24:27]
	v_mfma_f32_16x16x32_bf16 v[12:15], v[64:67], v[196:199], v[12:15]
	v_mfma_f32_16x16x32_bf16 v[8:11], v[72:75], v[196:199], v[8:11]
	v_mfma_f32_16x16x32_bf16 v[60:63], v[68:71], v[176:179], v[60:63]
	v_mfma_f32_16x16x32_bf16 v[56:59], v[76:79], v[176:179], v[56:59]
	v_mfma_f32_16x16x32_bf16 v[52:55], v[68:71], v[184:187], v[52:55]
	v_mfma_f32_16x16x32_bf16 v[44:47], v[76:79], v[184:187], v[44:47]
	v_mfma_f32_16x16x32_bf16 v[28:31], v[68:71], v[192:195], v[28:31]
	v_mfma_f32_16x16x32_bf16 v[24:27], v[76:79], v[192:195], v[24:27]
	v_mfma_f32_16x16x32_bf16 v[12:15], v[68:71], v[200:203], v[12:15]
	v_mfma_f32_16x16x32_bf16 v[8:11], v[76:79], v[200:203], v[8:11]
	v_mfma_f32_16x16x32_bf16 v[48:51], v[156:159], v[172:175], v[48:51]
	v_mfma_f32_16x16x32_bf16 v[40:43], v[164:167], v[172:175], v[40:43]
	v_mfma_f32_16x16x32_bf16 v[36:39], v[156:159], v[180:183], v[36:39]
	v_mfma_f32_16x16x32_bf16 v[32:35], v[164:167], v[180:183], v[32:35]
	v_mfma_f32_16x16x32_bf16 v[20:23], v[156:159], v[188:191], v[20:23]
	v_mfma_f32_16x16x32_bf16 v[16:19], v[164:167], v[188:191], v[16:19]
	v_mfma_f32_16x16x32_bf16 v[4:7], v[156:159], v[196:199], v[4:7]
	v_mfma_f32_16x16x32_bf16 v[0:3], v[164:167], v[196:199], v[0:3]
	v_mfma_f32_16x16x32_bf16 v[48:51], v[160:163], v[176:179], v[48:51]
	v_mfma_f32_16x16x32_bf16 v[40:43], v[168:171], v[176:179], v[40:43]
	v_mfma_f32_16x16x32_bf16 v[36:39], v[160:163], v[184:187], v[36:39]
	v_mfma_f32_16x16x32_bf16 v[32:35], v[168:171], v[184:187], v[32:35]
	v_mfma_f32_16x16x32_bf16 v[20:23], v[160:163], v[192:195], v[20:23]
	v_mfma_f32_16x16x32_bf16 v[16:19], v[168:171], v[192:195], v[16:19]
	v_mfma_f32_16x16x32_bf16 v[4:7], v[160:163], v[200:203], v[4:7]
	v_mfma_f32_16x16x32_bf16 v[0:3], v[168:171], v[200:203], v[0:3]
	s_barrier
	s_setprio 1
	s_add_i32 s84, 0, 0x18000
	s_add_i32 s85, 0, 0x1c000
	v_add_u32_e32 v76, s84, v228
	v_add_u32_e32 v168, s85, v228
	ds_read_b128 v[64:67], v76
	ds_read_b128 v[68:71], v76 offset:1024
	ds_read_b128 v[72:75], v76 offset:2048
	ds_read_b128 v[76:79], v76 offset:3072
	ds_read_b128 v[156:159], v168
	ds_read_b128 v[160:163], v168 offset:1024
	ds_read_b128 v[164:167], v168 offset:2048
	ds_read_b128 v[168:171], v168 offset:3072
	s_add_u32 s64, s64, 0x40000
	s_addc_u32 s65, s65, 0
	s_mov_b32 m0, s20
	v_lshl_add_u64 v[214:215], s[64:65], 0, v[150:151]
	ds_read_b128 v[172:175], v230 offset:32768
	ds_read_b128 v[176:179], v230 offset:33792
	ds_read_b128 v[180:183], v230 offset:34816
	ds_read_b128 v[184:187], v230 offset:35840
	ds_read_b128 v[188:191], v230 offset:36864
	ds_read_b128 v[192:195], v230 offset:37888
	ds_read_b128 v[196:199], v230 offset:38912
	ds_read_b128 v[200:203], v230 offset:39936
	global_load_lds_dwordx4 v[214:215], off
	v_lshl_add_u64 v[214:215], s[64:65], 0, v[148:149]
	s_mov_b32 m0, s21
	s_nop 0
	global_load_lds_dwordx4 v[214:215], off
	s_waitcnt vmcnt(8)
	s_waitcnt lgkmcnt(0)
	s_barrier
	s_setprio 0
	s_waitcnt lgkmcnt(0)
	v_mfma_f32_16x16x32_bf16 v[142:145], v[64:67], v[172:175], v[142:145]
	v_mfma_f32_16x16x32_bf16 v[138:141], v[72:75], v[172:175], v[138:141]
	v_mfma_f32_16x16x32_bf16 v[134:137], v[64:67], v[180:183], v[134:137]
	v_mfma_f32_16x16x32_bf16 v[124:127], v[72:75], v[180:183], v[124:127]
	v_mfma_f32_16x16x32_bf16 v[108:111], v[64:67], v[188:191], v[108:111]
	v_mfma_f32_16x16x32_bf16 v[104:107], v[72:75], v[188:191], v[104:107]
	v_mfma_f32_16x16x32_bf16 v[100:103], v[64:67], v[196:199], v[100:103]
	v_mfma_f32_16x16x32_bf16 v[92:95], v[72:75], v[196:199], v[92:95]
	v_mfma_f32_16x16x32_bf16 v[142:145], v[68:71], v[176:179], v[142:145]
	v_mfma_f32_16x16x32_bf16 v[138:141], v[76:79], v[176:179], v[138:141]
	v_mfma_f32_16x16x32_bf16 v[134:137], v[68:71], v[184:187], v[134:137]
	v_mfma_f32_16x16x32_bf16 v[124:127], v[76:79], v[184:187], v[124:127]
	v_mfma_f32_16x16x32_bf16 v[108:111], v[68:71], v[192:195], v[108:111]
	v_mfma_f32_16x16x32_bf16 v[104:107], v[76:79], v[192:195], v[104:107]
	v_mfma_f32_16x16x32_bf16 v[100:103], v[68:71], v[200:203], v[100:103]
	v_mfma_f32_16x16x32_bf16 v[92:95], v[76:79], v[200:203], v[92:95]
	v_mfma_f32_16x16x32_bf16 v[130:133], v[156:159], v[172:175], v[130:133]
	v_mfma_f32_16x16x32_bf16 v[120:123], v[164:167], v[172:175], v[120:123]
	v_mfma_f32_16x16x32_bf16 v[116:119], v[156:159], v[180:183], v[116:119]
	v_mfma_f32_16x16x32_bf16 v[112:115], v[164:167], v[180:183], v[112:115]
	v_mfma_f32_16x16x32_bf16 v[96:99], v[156:159], v[188:191], v[96:99]
	v_mfma_f32_16x16x32_bf16 v[88:91], v[164:167], v[188:191], v[88:91]
	v_mfma_f32_16x16x32_bf16 v[84:87], v[156:159], v[196:199], v[84:87]
	v_mfma_f32_16x16x32_bf16 v[80:83], v[164:167], v[196:199], v[80:83]
	v_mfma_f32_16x16x32_bf16 v[130:133], v[160:163], v[176:179], v[130:133]
	v_mfma_f32_16x16x32_bf16 v[120:123], v[168:171], v[176:179], v[120:123]
	v_mfma_f32_16x16x32_bf16 v[116:119], v[160:163], v[184:187], v[116:119]
	v_mfma_f32_16x16x32_bf16 v[112:115], v[168:171], v[184:187], v[112:115]
	v_mfma_f32_16x16x32_bf16 v[96:99], v[160:163], v[192:195], v[96:99]
	v_mfma_f32_16x16x32_bf16 v[88:91], v[168:171], v[192:195], v[88:91]
	v_mfma_f32_16x16x32_bf16 v[84:87], v[160:163], v[200:203], v[84:87]
	v_mfma_f32_16x16x32_bf16 v[80:83], v[168:171], v[200:203], v[80:83]
	s_barrier
; #define PG8_STAGE(bufoff, gbase, voff) do { _Pragma("unroll") for (int _i = 0; _i < 2; ++_i) \
;         __builtin_amdgcn_global_load_lds((const unsigned*)((const char*)(gbase) + (voff)[_i]), (PG8_LAS unsigned*)(lds + (bufoff) + ldsw + _i * 8192), 16, 0, 0); } while (0)
; #define PG8_LDA(dst, b, h) do { _Pragma("unroll") for (int m = 0; m < 4; ++m) _Pragma("unroll") for (int k = 0; k < 2; ++k) dst[m][k] = *(const PG8_LAS bf16x8*)(lds + PG8_SA(b, h) + aoff + m * 2048 + k * 1024); } while (0)
; #define PG8_LDB(dst, b, h) do { _Pragma("unroll") for (int n = 0; n < 2; ++n) _Pragma("unroll") for (int k = 0; k < 2; ++k) dst[n][k] = *(const PG8_LAS bf16x8*)(lds + PG8_SB(b, h) + boff + n * 2048 + k * 1024); } while (0)
; #define PG8_MMA(ai, bj, At, Bt) do { __builtin_amdgcn_s_setprio(1); _Pragma("unroll") for (int m = 0; m < 4; ++m) _Pragma("unroll") for (int n = 0; n < 2; ++n) _Pragma("unroll") for (int k = 0; k < 2; ++k) \
;         acc[ai][bj][m][n] = __builtin_amdgcn_mfma_f32_16x16x32_bf16(Bt[n][k], At[m][k], acc[ai][bj][m][n], 0, 0, 0); __builtin_amdgcn_s_setprio(0); } while (0)
; template <class Epi, class Sched, bool ALIGN_EPI = false, bool SP2 = false>
; __device__ __forceinline__ void gemm_phase(PG8_LAS unsigned char* lds, const Gemm g, const Sched& S, const Epi& E) {
;     ...
;             PG8_LDB(B0, 0, 0); PG8_LDB(B1, 0, 1); PG8_SCHED; PG8_LDA(At, 0, 0); PG8_STAGE(PG8_SA(1, 1), a1 + hstep, voffA);
;             PG8_WAIT_V(8); PG8_WAIT_L(0); PG8_BAR; PG8_MMA(0, 0, At, B0); PG8_MMA(0, 1, At, B1); PG8_BAR; PG8_SCHED;
;             PG8_LDA(At, 0, 1); PG8_STAGE(PG8_SB(0, 0), b2, voffB); PG8_STAGE(PG8_SB(0, 1), b2 + hstep, voffB); PG8_STAGE(PG8_SA(0, 0), a2, voffA);
;             PG8_WAIT_V(8); PG8_WAIT_L(0); PG8_BAR; PG8_MMA(1, 0, At, B0); PG8_MMA(1, 1, At, B1); PG8_BAR; PG8_SCHED;
;             PG8_LDB(B0, 1, 0); PG8_LDB(B1, 1, 1); PG8_SCHED; PG8_LDA(At, 1, 0); PG8_STAGE(PG8_SA(0, 1), a2 + hstep, voffA);
;             PG8_WAIT_V(8); PG8_WAIT_L(0); PG8_BAR; PG8_MMA(0, 0, At, B0); PG8_MMA(0, 1, At, B1); PG8_BAR; PG8_SCHED;
;             PG8_LDA(At, 1, 1); PG8_STAGE(PG8_SB(1, 0), b3, voffB); PG8_STAGE(PG8_SB(1, 1), b3 + hstep, voffB); PG8_STAGE(PG8_SA(1, 0), a3, voffA);
;             PG8_WAIT_V(8); PG8_WAIT_L(0); PG8_BAR; PG8_MMA(1, 0, At, B0); PG8_MMA(1, 1, At, B1); PG8_BAR; PG8_SCHED;
;     ...
;         if constexpr (ALIGN_EPI) { if (wr == 0) PG8_BAR; }
	s_setprio 1
	s_add_i32 s64, s84, s17
	v_lshl_add_u64 v[204:205], v[204:205], 0, s[90:91]
	s_mov_b32 m0, s64
	ds_read_b128 v[172:175], v230 offset:49152
	ds_read_b128 v[176:179], v230 offset:50176
	ds_read_b128 v[180:183], v230 offset:51200
	ds_read_b128 v[184:187], v230 offset:52224
	ds_read_b128 v[188:191], v230 offset:53248
	ds_read_b128 v[192:195], v230 offset:54272
	ds_read_b128 v[196:199], v230 offset:55296
	ds_read_b128 v[200:203], v230 offset:56320
	global_load_lds_dwordx4 v[204:205], off
	s_add_i32 m0, s64, 0x2000
	s_add_u32 s58, s58, 0x40080
	v_lshl_add_u64 v[204:205], v[206:207], 0, s[90:91]
	s_addc_u32 s59, s59, 0
	s_add_i32 s64, s85, s17
	global_load_lds_dwordx4 v[204:205], off
	v_lshl_add_u64 v[204:205], s[58:59], 0, v[128:129]
	s_mov_b32 m0, s64
	s_nop 0
	global_load_lds_dwordx4 v[204:205], off
	v_lshl_add_u64 v[204:205], s[58:59], 0, v[146:147]
	s_add_i32 m0, s64, 0x2000
	s_nop 0
	global_load_lds_dwordx4 v[204:205], off
	v_lshl_add_u64 v[204:205], v[208:209], 0, s[90:91]
	s_mov_b32 m0, s28
	s_nop 0
	global_load_lds_dwordx4 v[204:205], off
	v_lshl_add_u64 v[204:205], v[210:211], 0, s[90:91]
	s_mov_b32 m0, s29
	s_nop 0
	global_load_lds_dwordx4 v[204:205], off
	s_waitcnt vmcnt(8)
	s_waitcnt lgkmcnt(0)
	s_barrier
	s_setprio 0
	s_waitcnt lgkmcnt(0)
	v_mfma_f32_16x16x32_bf16 v[60:63], v[64:67], v[172:175], v[60:63]
	v_mfma_f32_16x16x32_bf16 v[56:59], v[72:75], v[172:175], v[56:59]
	v_mfma_f32_16x16x32_bf16 v[52:55], v[64:67], v[180:183], v[52:55]
	v_mfma_f32_16x16x32_bf16 v[44:47], v[72:75], v[180:183], v[44:47]
	v_mfma_f32_16x16x32_bf16 v[28:31], v[64:67], v[188:191], v[28:31]
	v_mfma_f32_16x16x32_bf16 v[24:27], v[72:75], v[188:191], v[24:27]
	v_mfma_f32_16x16x32_bf16 v[12:15], v[64:67], v[196:199], v[12:15]
	v_mfma_f32_16x16x32_bf16 v[8:11], v[72:75], v[196:199], v[8:11]
	v_mfma_f32_16x16x32_bf16 v[60:63], v[68:71], v[176:179], v[60:63]
	v_mfma_f32_16x16x32_bf16 v[56:59], v[76:79], v[176:179], v[56:59]
	v_mfma_f32_16x16x32_bf16 v[52:55], v[68:71], v[184:187], v[52:55]
	v_mfma_f32_16x16x32_bf16 v[44:47], v[76:79], v[184:187], v[44:47]
	v_mfma_f32_16x16x32_bf16 v[28:31], v[68:71], v[192:195], v[28:31]
	v_mfma_f32_16x16x32_bf16 v[24:27], v[76:79], v[192:195], v[24:27]
	v_mfma_f32_16x16x32_bf16 v[12:15], v[68:71], v[200:203], v[12:15]
	v_mfma_f32_16x16x32_bf16 v[8:11], v[76:79], v[200:203], v[8:11]
	v_mfma_f32_16x16x32_bf16 v[48:51], v[156:159], v[172:175], v[48:51]
	v_mfma_f32_16x16x32_bf16 v[40:43], v[164:167], v[172:175], v[40:43]
	v_mfma_f32_16x16x32_bf16 v[36:39], v[156:159], v[180:183], v[36:39]
	v_mfma_f32_16x16x32_bf16 v[32:35], v[164:167], v[180:183], v[32:35]
	v_mfma_f32_16x16x32_bf16 v[20:23], v[156:159], v[188:191], v[20:23]
	v_mfma_f32_16x16x32_bf16 v[16:19], v[164:167], v[188:191], v[16:19]
	v_mfma_f32_16x16x32_bf16 v[4:7], v[156:159], v[196:199], v[4:7]
	v_mfma_f32_16x16x32_bf16 v[0:3], v[164:167], v[196:199], v[0:3]
	v_mfma_f32_16x16x32_bf16 v[48:51], v[160:163], v[176:179], v[48:51]
	v_mfma_f32_16x16x32_bf16 v[40:43], v[168:171], v[176:179], v[40:43]
	v_mfma_f32_16x16x32_bf16 v[36:39], v[160:163], v[184:187], v[36:39]
	v_mfma_f32_16x16x32_bf16 v[32:35], v[168:171], v[184:187], v[32:35]
	v_mfma_f32_16x16x32_bf16 v[20:23], v[160:163], v[192:195], v[20:23]
	v_mfma_f32_16x16x32_bf16 v[16:19], v[168:171], v[192:195], v[16:19]
	v_mfma_f32_16x16x32_bf16 v[4:7], v[160:163], v[200:203], v[4:7]
	v_mfma_f32_16x16x32_bf16 v[0:3], v[168:171], v[200:203], v[0:3]
	s_barrier
	s_setprio 1
	s_add_i32 s94, s94, 2
	s_add_u32 vcc_lo, vcc_lo, 0x100
	s_addc_u32 vcc_hi, vcc_hi, 0
	s_add_u32 s88, s88, 0x100
	s_addc_u32 s93, s93, 0
	s_cmp_gt_u32 s94, 13
	s_cbranch_scc0 .LBB0_598
	s_setprio 0
	s_and_b64 vcc, exec, s[72:73]
	s_cbranch_vccz .LBB0_601
	s_barrier

; #define PG8_STAGE(bufoff, gbase, voff) do { _Pragma("unroll") for (int _i = 0; _i < 2; ++_i) \
;         __builtin_amdgcn_global_load_lds((const unsigned*)((const char*)(gbase) + (voff)[_i]), (PG8_LAS unsigned*)(lds + (bufoff) + ldsw + _i * 8192), 16, 0, 0); } while (0)
; #define PG8_LDA(dst, b, h) do { _Pragma("unroll") for (int m = 0; m < 4; ++m) _Pragma("unroll") for (int k = 0; k < 2; ++k) dst[m][k] = *(const PG8_LAS bf16x8*)(lds + PG8_SA(b, h) + aoff + m * 2048 + k * 1024); } while (0)
; #define PG8_LDB(dst, b, h) do { _Pragma("unroll") for (int n = 0; n < 2; ++n) _Pragma("unroll") for (int k = 0; k < 2; ++k) dst[n][k] = *(const PG8_LAS bf16x8*)(lds + PG8_SB(b, h) + boff + n * 2048 + k * 1024); } while (0)
; #define PG8_MMA(ai, bj, At, Bt) do { __builtin_amdgcn_s_setprio(1); _Pragma("unroll") for (int m = 0; m < 4; ++m) _Pragma("unroll") for (int n = 0; n < 2; ++n) _Pragma("unroll") for (int k = 0; k < 2; ++k) \
;         acc[ai][bj][m][n] = __builtin_amdgcn_mfma_f32_16x16x32_bf16(Bt[n][k], At[m][k], acc[ai][bj][m][n], 0, 0, 0); __builtin_amdgcn_s_setprio(0); } while (0)
; #define PG8_WAIT_V(n) asm volatile("s_waitcnt vmcnt(" #n ")" ::: "memory")
; #define PG8_WAIT_L(n) asm volatile("s_waitcnt lgkmcnt(" #n ")" ::: "memory")
; #define PG8_BAR __builtin_amdgcn_s_barrier()
; #define PG8_SCHED __builtin_amdgcn_sched_barrier(0)
; template <class Epi, class Sched, bool ALIGN_EPI = false, bool SP2 = false>
; __device__ __forceinline__ void gemm_phase(PG8_LAS unsigned char* lds, const Gemm g, const Sched& S, const Epi& E) {
;     ...
;             const bool last = (t == nt - 2);
;             const char* a1 = cA + (size_t)(t + 1) * kstep;
;             const char* a2 = last ? nA : cA + (size_t)(t + 2) * kstep; const char* b2 = last ? nB : cB + (size_t)(t + 2) * kstep;
;             const char* a3 = a2 + kstep; const char* b3 = b2 + kstep;
;             if (last && has_next) S.a_ready(nxt);
;             if constexpr (SP2) {
;             PG8_LDB(B0, 0, 0); PG8_LDB(B1, 0, 1); PG8_SCHED; PG8_LDA(At, 0, 0); PG8_STAGE(PG8_SA(1, 1), a1 + hstep, voffA);
;             PG8_WAIT_V(8); PG8_WAIT_L(0); PG8_BAR; PG8_MMA(0, 0, At, B0); PG8_MMA(0, 1, At, B1); PG8_BAR; PG8_SCHED;
.LBB0_813:
	s_add_u32 s8, s66, 0xfffc0080
	s_addc_u32 s37, s67, -1
	s_add_i32 s49, 0, 0x10000
	s_cmp_eq_u32 s36, 12
	s_cselect_b32 s65, s28, s37
	s_cselect_b32 s64, s29, s8
	s_cselect_b32 s59, s30, s35
	s_cselect_b32 s58, s31, s34
	s_add_i32 s8, 0, 0x14000
	v_add_u32_e32 v156, s49, v145
	v_add_u32_e32 v172, s8, v145
	ds_read_b128 v[140:143], v156
	ds_read_b128 v[148:151], v156 offset:1024
	ds_read_b128 v[152:155], v156 offset:2048
	ds_read_b128 v[156:159], v156 offset:3072
	ds_read_b128 v[160:163], v172
	ds_read_b128 v[164:167], v172 offset:1024
	ds_read_b128 v[168:171], v172 offset:2048
	ds_read_b128 v[172:175], v172 offset:3072
	v_lshl_add_u64 v[208:209], s[66:67], 0, v[136:137]
	s_add_i32 m0, s18, 0xc000
	ds_read_b128 v[176:179], v147
	ds_read_b128 v[180:183], v147 offset:1024
	ds_read_b128 v[184:187], v147 offset:2048
	ds_read_b128 v[188:191], v147 offset:3072
	ds_read_b128 v[192:195], v147 offset:4096
	ds_read_b128 v[196:199], v147 offset:5120
	ds_read_b128 v[200:203], v147 offset:6144
	ds_read_b128 v[204:207], v147 offset:7168
	global_load_lds_dwordx4 v[208:209], off
	v_lshl_add_u64 v[208:209], s[66:67], 0, v[138:139]
	s_add_i32 m0, s18, 0xe000
	s_nop 0
	global_load_lds_dwordx4 v[208:209], off
	s_waitcnt vmcnt(8)
	s_waitcnt lgkmcnt(0)
	s_barrier
	s_setprio 0
	s_waitcnt lgkmcnt(0)
	v_mfma_f32_16x16x32_bf16 v[124:127], v[140:143], v[176:179], v[124:127]
	v_mfma_f32_16x16x32_bf16 v[116:119], v[152:155], v[176:179], v[116:119]
	v_mfma_f32_16x16x32_bf16 v[108:111], v[140:143], v[184:187], v[108:111]
	v_mfma_f32_16x16x32_bf16 v[100:103], v[152:155], v[184:187], v[100:103]
	v_mfma_f32_16x16x32_bf16 v[92:95], v[140:143], v[192:195], v[92:95]
	v_mfma_f32_16x16x32_bf16 v[84:87], v[152:155], v[192:195], v[84:87]
	v_mfma_f32_16x16x32_bf16 v[76:79], v[140:143], v[200:203], v[76:79]
	v_mfma_f32_16x16x32_bf16 v[68:71], v[152:155], v[200:203], v[68:71]
	v_mfma_f32_16x16x32_bf16 v[124:127], v[148:151], v[180:183], v[124:127]
	v_mfma_f32_16x16x32_bf16 v[116:119], v[156:159], v[180:183], v[116:119]
	v_mfma_f32_16x16x32_bf16 v[108:111], v[148:151], v[188:191], v[108:111]
	v_mfma_f32_16x16x32_bf16 v[100:103], v[156:159], v[188:191], v[100:103]
	v_mfma_f32_16x16x32_bf16 v[92:95], v[148:151], v[196:199], v[92:95]
	v_mfma_f32_16x16x32_bf16 v[84:87], v[156:159], v[196:199], v[84:87]
	v_mfma_f32_16x16x32_bf16 v[76:79], v[148:151], v[204:207], v[76:79]
	v_mfma_f32_16x16x32_bf16 v[68:71], v[156:159], v[204:207], v[68:71]
	v_mfma_f32_16x16x32_bf16 v[120:123], v[160:163], v[176:179], v[120:123]
	v_mfma_f32_16x16x32_bf16 v[112:115], v[168:171], v[176:179], v[112:115]
	v_mfma_f32_16x16x32_bf16 v[104:107], v[160:163], v[184:187], v[104:107]
	v_mfma_f32_16x16x32_bf16 v[96:99], v[168:171], v[184:187], v[96:99]
	v_mfma_f32_16x16x32_bf16 v[88:91], v[160:163], v[192:195], v[88:91]
	v_mfma_f32_16x16x32_bf16 v[80:83], v[168:171], v[192:195], v[80:83]
	v_mfma_f32_16x16x32_bf16 v[72:75], v[160:163], v[200:203], v[72:75]
	v_mfma_f32_16x16x32_bf16 v[64:67], v[168:171], v[200:203], v[64:67]
	v_mfma_f32_16x16x32_bf16 v[120:123], v[164:167], v[180:183], v[120:123]
	v_mfma_f32_16x16x32_bf16 v[112:115], v[172:175], v[180:183], v[112:115]
	v_mfma_f32_16x16x32_bf16 v[104:107], v[164:167], v[188:191], v[104:107]
	v_mfma_f32_16x16x32_bf16 v[96:99], v[172:175], v[188:191], v[96:99]
	v_mfma_f32_16x16x32_bf16 v[88:91], v[164:167], v[196:199], v[88:91]
	v_mfma_f32_16x16x32_bf16 v[80:83], v[172:175], v[196:199], v[80:83]
	v_mfma_f32_16x16x32_bf16 v[72:75], v[164:167], v[204:207], v[72:75]
	v_mfma_f32_16x16x32_bf16 v[64:67], v[172:175], v[204:207], v[64:67]
	s_barrier
	s_setprio 1
	s_add_i32 s37, s49, s17
	v_lshl_add_u64 v[208:209], s[58:59], 0, v[128:129]
	s_mov_b32 m0, s37
	ds_read_b128 v[176:179], v147 offset:16384
	ds_read_b128 v[180:183], v147 offset:17408
	ds_read_b128 v[184:187], v147 offset:18432
	ds_read_b128 v[188:191], v147 offset:19456
	ds_read_b128 v[192:195], v147 offset:20480
	ds_read_b128 v[196:199], v147 offset:21504
	ds_read_b128 v[200:203], v147 offset:22528
	ds_read_b128 v[204:207], v147 offset:23552
	global_load_lds_dwordx4 v[208:209], off
	s_add_i32 m0, s37, 0x2000
	s_add_u32 s72, s58, 0x40000
	v_lshl_add_u64 v[210:211], s[58:59], 0, v[130:131]
	s_addc_u32 s73, s59, 0
	s_add_i32 s8, s8, s17
	global_load_lds_dwordx4 v[210:211], off
	v_lshl_add_u64 v[214:215], s[72:73], 0, v[128:129]
	s_mov_b32 m0, s8
	v_lshl_add_u64 v[222:223], s[64:65], 0, v[132:133]
	global_load_lds_dwordx4 v[214:215], off
	v_lshl_add_u64 v[214:215], s[72:73], 0, v[130:131]
	s_add_i32 m0, s8, 0x2000
	s_nop 0
	global_load_lds_dwordx4 v[214:215], off
	v_lshl_add_u64 v[214:215], s[64:65], 0, v[134:135]
	s_mov_b32 m0, s18
	s_nop 0
	global_load_lds_dwordx4 v[214:215], off
	s_mov_b32 m0, s19
	s_nop 0
	global_load_lds_dwordx4 v[222:223], off
	s_waitcnt vmcnt(8)
	s_waitcnt lgkmcnt(0)
	s_barrier
; #define PG8_STAGE(bufoff, gbase, voff) do { _Pragma("unroll") for (int _i = 0; _i < 2; ++_i) \
;         __builtin_amdgcn_global_load_lds((const unsigned*)((const char*)(gbase) + (voff)[_i]), (PG8_LAS unsigned*)(lds + (bufoff) + ldsw + _i * 8192), 16, 0, 0); } while (0)
; #define PG8_LDA(dst, b, h) do { _Pragma("unroll") for (int m = 0; m < 4; ++m) _Pragma("unroll") for (int k = 0; k < 2; ++k) dst[m][k] = *(const PG8_LAS bf16x8*)(lds + PG8_SA(b, h) + aoff + m * 2048 + k * 1024); } while (0)
; #define PG8_LDB(dst, b, h) do { _Pragma("unroll") for (int n = 0; n < 2; ++n) _Pragma("unroll") for (int k = 0; k < 2; ++k) dst[n][k] = *(const PG8_LAS bf16x8*)(lds + PG8_SB(b, h) + boff + n * 2048 + k * 1024); } while (0)
; #define PG8_MMA(ai, bj, At, Bt) do { __builtin_amdgcn_s_setprio(1); _Pragma("unroll") for (int m = 0; m < 4; ++m) _Pragma("unroll") for (int n = 0; n < 2; ++n) _Pragma("unroll") for (int k = 0; k < 2; ++k) \
;         acc[ai][bj][m][n] = __builtin_amdgcn_mfma_f32_16x16x32_bf16(Bt[n][k], At[m][k], acc[ai][bj][m][n], 0, 0, 0); __builtin_amdgcn_s_setprio(0); } while (0)
; #define PG8_WAIT_V(n) asm volatile("s_waitcnt vmcnt(" #n ")" ::: "memory")
; template <class Epi, class Sched, bool ALIGN_EPI = false, bool SP2 = false>
; __device__ __forceinline__ void gemm_phase(PG8_LAS unsigned char* lds, const Gemm g, const Sched& S, const Epi& E) {
;     ...
;             PG8_LDB(B0, 0, 0); PG8_LDB(B1, 0, 1); PG8_SCHED; PG8_LDA(At, 0, 0); PG8_STAGE(PG8_SA(1, 1), a1 + hstep, voffA);
;             PG8_WAIT_V(8); PG8_WAIT_L(0); PG8_BAR; PG8_MMA(0, 0, At, B0); PG8_MMA(0, 1, At, B1); PG8_BAR; PG8_SCHED;
;             PG8_LDA(At, 0, 1); PG8_STAGE(PG8_SB(0, 0), b2, voffB); PG8_STAGE(PG8_SB(0, 1), b2 + hstep, voffB); PG8_STAGE(PG8_SA(0, 0), a2, voffA);
;             PG8_WAIT_V(8); PG8_WAIT_L(0); PG8_BAR; PG8_MMA(1, 0, At, B0); PG8_MMA(1, 1, At, B1); PG8_BAR; PG8_SCHED;
;             PG8_LDB(B0, 1, 0); PG8_LDB(B1, 1, 1); PG8_SCHED; PG8_LDA(At, 1, 0); PG8_STAGE(PG8_SA(0, 1), a2 + hstep, voffA);
;             PG8_WAIT_V(8); PG8_WAIT_L(0); PG8_BAR; PG8_MMA(0, 0, At, B0); PG8_MMA(0, 1, At, B1); PG8_BAR; PG8_SCHED;
;             PG8_LDA(At, 1, 1); PG8_STAGE(PG8_SB(1, 0), b3, voffB); PG8_STAGE(PG8_SB(1, 1), b3 + hstep, voffB); PG8_STAGE(PG8_SA(1, 0), a3, voffA);
;             PG8_WAIT_V(8); PG8_WAIT_L(0); PG8_BAR; PG8_MMA(1, 0, At, B0); PG8_MMA(1, 1, At, B1); PG8_BAR; PG8_SCHED;
	s_setprio 0
	s_waitcnt lgkmcnt(0)
	v_mfma_f32_16x16x32_bf16 v[60:63], v[140:143], v[176:179], v[60:63]
	v_mfma_f32_16x16x32_bf16 v[52:55], v[152:155], v[176:179], v[52:55]
	v_mfma_f32_16x16x32_bf16 v[44:47], v[140:143], v[184:187], v[44:47]
	v_mfma_f32_16x16x32_bf16 v[36:39], v[152:155], v[184:187], v[36:39]
	v_mfma_f32_16x16x32_bf16 v[28:31], v[140:143], v[192:195], v[28:31]
	v_mfma_f32_16x16x32_bf16 v[20:23], v[152:155], v[192:195], v[20:23]
	v_mfma_f32_16x16x32_bf16 v[12:15], v[140:143], v[200:203], v[12:15]
	v_mfma_f32_16x16x32_bf16 v[4:7], v[152:155], v[200:203], v[4:7]
	v_mfma_f32_16x16x32_bf16 v[60:63], v[148:151], v[180:183], v[60:63]
	v_mfma_f32_16x16x32_bf16 v[52:55], v[156:159], v[180:183], v[52:55]
	v_mfma_f32_16x16x32_bf16 v[44:47], v[148:151], v[188:191], v[44:47]
	v_mfma_f32_16x16x32_bf16 v[36:39], v[156:159], v[188:191], v[36:39]
	v_mfma_f32_16x16x32_bf16 v[28:31], v[148:151], v[196:199], v[28:31]
	v_mfma_f32_16x16x32_bf16 v[20:23], v[156:159], v[196:199], v[20:23]
	v_mfma_f32_16x16x32_bf16 v[12:15], v[148:151], v[204:207], v[12:15]
	v_mfma_f32_16x16x32_bf16 v[4:7], v[156:159], v[204:207], v[4:7]
	v_mfma_f32_16x16x32_bf16 v[56:59], v[160:163], v[176:179], v[56:59]
	v_mfma_f32_16x16x32_bf16 v[48:51], v[168:171], v[176:179], v[48:51]
	v_mfma_f32_16x16x32_bf16 v[40:43], v[160:163], v[184:187], v[40:43]
	v_mfma_f32_16x16x32_bf16 v[32:35], v[168:171], v[184:187], v[32:35]
	v_mfma_f32_16x16x32_bf16 v[24:27], v[160:163], v[192:195], v[24:27]
	v_mfma_f32_16x16x32_bf16 v[16:19], v[168:171], v[192:195], v[16:19]
	v_mfma_f32_16x16x32_bf16 v[8:11], v[160:163], v[200:203], v[8:11]
	v_mfma_f32_16x16x32_bf16 v[0:3], v[168:171], v[200:203], v[0:3]
	v_mfma_f32_16x16x32_bf16 v[56:59], v[164:167], v[180:183], v[56:59]
	v_mfma_f32_16x16x32_bf16 v[48:51], v[172:175], v[180:183], v[48:51]
	v_mfma_f32_16x16x32_bf16 v[40:43], v[164:167], v[188:191], v[40:43]
	v_mfma_f32_16x16x32_bf16 v[32:35], v[172:175], v[188:191], v[32:35]
	v_mfma_f32_16x16x32_bf16 v[24:27], v[164:167], v[196:199], v[24:27]
	v_mfma_f32_16x16x32_bf16 v[16:19], v[172:175], v[196:199], v[16:19]
	v_mfma_f32_16x16x32_bf16 v[8:11], v[164:167], v[204:207], v[8:11]
	v_mfma_f32_16x16x32_bf16 v[0:3], v[172:175], v[204:207], v[0:3]
	s_barrier
	s_setprio 1
	s_add_i32 s8, 0, 0x18000
	s_add_i32 s37, 0, 0x1c000
	v_add_u32_e32 v156, s8, v145
	v_add_u32_e32 v172, s37, v145
	ds_read_b128 v[140:143], v156
	ds_read_b128 v[148:151], v156 offset:1024
	ds_read_b128 v[152:155], v156 offset:2048
	ds_read_b128 v[156:159], v156 offset:3072
	ds_read_b128 v[160:163], v172
	ds_read_b128 v[164:167], v172 offset:1024
	ds_read_b128 v[168:171], v172 offset:2048
	ds_read_b128 v[172:175], v172 offset:3072
	s_add_u32 s64, s64, 0x40000
	s_addc_u32 s65, s65, 0
	s_mov_b32 m0, s20
	v_lshl_add_u64 v[228:229], s[64:65], 0, v[134:135]
	ds_read_b128 v[176:179], v147 offset:32768
	ds_read_b128 v[180:183], v147 offset:33792
	ds_read_b128 v[184:187], v147 offset:34816
	ds_read_b128 v[188:191], v147 offset:35840
	ds_read_b128 v[192:195], v147 offset:36864
	ds_read_b128 v[196:199], v147 offset:37888
	ds_read_b128 v[200:203], v147 offset:38912
	ds_read_b128 v[204:207], v147 offset:39936
	global_load_lds_dwordx4 v[228:229], off
	v_lshl_add_u64 v[228:229], s[64:65], 0, v[132:133]
	s_mov_b32 m0, s21
	s_nop 0
	global_load_lds_dwordx4 v[228:229], off
	s_waitcnt vmcnt(8)
	s_waitcnt lgkmcnt(0)
	s_barrier
	s_setprio 0
	s_waitcnt lgkmcnt(0)
	v_mfma_f32_16x16x32_bf16 v[124:127], v[140:143], v[176:179], v[124:127]
	v_mfma_f32_16x16x32_bf16 v[116:119], v[152:155], v[176:179], v[116:119]
	v_mfma_f32_16x16x32_bf16 v[108:111], v[140:143], v[184:187], v[108:111]
	v_mfma_f32_16x16x32_bf16 v[100:103], v[152:155], v[184:187], v[100:103]
	v_mfma_f32_16x16x32_bf16 v[92:95], v[140:143], v[192:195], v[92:95]
	v_mfma_f32_16x16x32_bf16 v[84:87], v[152:155], v[192:195], v[84:87]
	v_mfma_f32_16x16x32_bf16 v[76:79], v[140:143], v[200:203], v[76:79]
	v_mfma_f32_16x16x32_bf16 v[68:71], v[152:155], v[200:203], v[68:71]
	v_mfma_f32_16x16x32_bf16 v[124:127], v[148:151], v[180:183], v[124:127]
	v_mfma_f32_16x16x32_bf16 v[116:119], v[156:159], v[180:183], v[116:119]
	v_mfma_f32_16x16x32_bf16 v[108:111], v[148:151], v[188:191], v[108:111]
	v_mfma_f32_16x16x32_bf16 v[100:103], v[156:159], v[188:191], v[100:103]
	v_mfma_f32_16x16x32_bf16 v[92:95], v[148:151], v[196:199], v[92:95]
	v_mfma_f32_16x16x32_bf16 v[84:87], v[156:159], v[196:199], v[84:87]
	v_mfma_f32_16x16x32_bf16 v[76:79], v[148:151], v[204:207], v[76:79]
	v_mfma_f32_16x16x32_bf16 v[68:71], v[156:159], v[204:207], v[68:71]
	v_mfma_f32_16x16x32_bf16 v[120:123], v[160:163], v[176:179], v[120:123]
	v_mfma_f32_16x16x32_bf16 v[112:115], v[168:171], v[176:179], v[112:115]
	v_mfma_f32_16x16x32_bf16 v[104:107], v[160:163], v[184:187], v[104:107]
	v_mfma_f32_16x16x32_bf16 v[96:99], v[168:171], v[184:187], v[96:99]
	v_mfma_f32_16x16x32_bf16 v[88:91], v[160:163], v[192:195], v[88:91]
	v_mfma_f32_16x16x32_bf16 v[80:83], v[168:171], v[192:195], v[80:83]
	v_mfma_f32_16x16x32_bf16 v[72:75], v[160:163], v[200:203], v[72:75]
	v_mfma_f32_16x16x32_bf16 v[64:67], v[168:171], v[200:203], v[64:67]
	v_mfma_f32_16x16x32_bf16 v[120:123], v[164:167], v[180:183], v[120:123]
	v_mfma_f32_16x16x32_bf16 v[112:115], v[172:175], v[180:183], v[112:115]
	v_mfma_f32_16x16x32_bf16 v[104:107], v[164:167], v[188:191], v[104:107]
	v_mfma_f32_16x16x32_bf16 v[96:99], v[172:175], v[188:191], v[96:99]
	v_mfma_f32_16x16x32_bf16 v[88:91], v[164:167], v[196:199], v[88:91]
	v_mfma_f32_16x16x32_bf16 v[80:83], v[172:175], v[196:199], v[80:83]
	v_mfma_f32_16x16x32_bf16 v[72:75], v[164:167], v[204:207], v[72:75]
	v_mfma_f32_16x16x32_bf16 v[64:67], v[172:175], v[204:207], v[64:67]
	s_barrier
; #define PG8_STAGE(bufoff, gbase, voff) do { _Pragma("unroll") for (int _i = 0; _i < 2; ++_i) \
;         __builtin_amdgcn_global_load_lds((const unsigned*)((const char*)(gbase) + (voff)[_i]), (PG8_LAS unsigned*)(lds + (bufoff) + ldsw + _i * 8192), 16, 0, 0); } while (0)
; #define PG8_LDA(dst, b, h) do { _Pragma("unroll") for (int m = 0; m < 4; ++m) _Pragma("unroll") for (int k = 0; k < 2; ++k) dst[m][k] = *(const PG8_LAS bf16x8*)(lds + PG8_SA(b, h) + aoff + m * 2048 + k * 1024); } while (0)
; #define PG8_LDB(dst, b, h) do { _Pragma("unroll") for (int n = 0; n < 2; ++n) _Pragma("unroll") for (int k = 0; k < 2; ++k) dst[n][k] = *(const PG8_LAS bf16x8*)(lds + PG8_SB(b, h) + boff + n * 2048 + k * 1024); } while (0)
; #define PG8_MMA(ai, bj, At, Bt) do { __builtin_amdgcn_s_setprio(1); _Pragma("unroll") for (int m = 0; m < 4; ++m) _Pragma("unroll") for (int n = 0; n < 2; ++n) _Pragma("unroll") for (int k = 0; k < 2; ++k) \
;         acc[ai][bj][m][n] = __builtin_amdgcn_mfma_f32_16x16x32_bf16(Bt[n][k], At[m][k], acc[ai][bj][m][n], 0, 0, 0); __builtin_amdgcn_s_setprio(0); } while (0)
; template <class Epi, class Sched, bool ALIGN_EPI = false, bool SP2 = false>
; __device__ __forceinline__ void gemm_phase(PG8_LAS unsigned char* lds, const Gemm g, const Sched& S, const Epi& E) {
;     ...
;             PG8_LDB(B0, 0, 0); PG8_LDB(B1, 0, 1); PG8_SCHED; PG8_LDA(At, 0, 0); PG8_STAGE(PG8_SA(1, 1), a1 + hstep, voffA);
;             PG8_WAIT_V(8); PG8_WAIT_L(0); PG8_BAR; PG8_MMA(0, 0, At, B0); PG8_MMA(0, 1, At, B1); PG8_BAR; PG8_SCHED;
;             PG8_LDA(At, 0, 1); PG8_STAGE(PG8_SB(0, 0), b2, voffB); PG8_STAGE(PG8_SB(0, 1), b2 + hstep, voffB); PG8_STAGE(PG8_SA(0, 0), a2, voffA);
;             PG8_WAIT_V(8); PG8_WAIT_L(0); PG8_BAR; PG8_MMA(1, 0, At, B0); PG8_MMA(1, 1, At, B1); PG8_BAR; PG8_SCHED;
;             PG8_LDB(B0, 1, 0); PG8_LDB(B1, 1, 1); PG8_SCHED; PG8_LDA(At, 1, 0); PG8_STAGE(PG8_SA(0, 1), a2 + hstep, voffA);
;             PG8_WAIT_V(8); PG8_WAIT_L(0); PG8_BAR; PG8_MMA(0, 0, At, B0); PG8_MMA(0, 1, At, B1); PG8_BAR; PG8_SCHED;
;             PG8_LDA(At, 1, 1); PG8_STAGE(PG8_SB(1, 0), b3, voffB); PG8_STAGE(PG8_SB(1, 1), b3 + hstep, voffB); PG8_STAGE(PG8_SA(1, 0), a3, voffA);
;             PG8_WAIT_V(8); PG8_WAIT_L(0); PG8_BAR; PG8_MMA(1, 0, At, B0); PG8_MMA(1, 1, At, B1); PG8_BAR; PG8_SCHED;
;     ...
;         if constexpr (ALIGN_EPI) { if (wr == 0) PG8_BAR; }
	s_setprio 1
	s_add_i32 s8, s8, s17
	v_lshl_add_u64 v[208:209], v[208:209], 0, s[90:91]
	s_mov_b32 m0, s8
	ds_read_b128 v[176:179], v147 offset:49152
	ds_read_b128 v[180:183], v147 offset:50176
	ds_read_b128 v[184:187], v147 offset:51200
	ds_read_b128 v[188:191], v147 offset:52224
	ds_read_b128 v[192:195], v147 offset:53248
	ds_read_b128 v[196:199], v147 offset:54272
	ds_read_b128 v[200:203], v147 offset:55296
	ds_read_b128 v[204:207], v147 offset:56320
	global_load_lds_dwordx4 v[208:209], off
	s_add_i32 m0, s8, 0x2000
	s_add_u32 s58, s58, 0x40080
	v_lshl_add_u64 v[208:209], v[210:211], 0, s[90:91]
	s_addc_u32 s59, s59, 0
	s_add_i32 s8, s37, s17
	global_load_lds_dwordx4 v[208:209], off
	v_lshl_add_u64 v[208:209], s[58:59], 0, v[128:129]
	s_mov_b32 m0, s8
	s_nop 0
	global_load_lds_dwordx4 v[208:209], off
	v_lshl_add_u64 v[208:209], s[58:59], 0, v[130:131]
	s_add_i32 m0, s8, 0x2000
	s_nop 0
	global_load_lds_dwordx4 v[208:209], off
	v_lshl_add_u64 v[208:209], v[214:215], 0, s[90:91]
	s_mov_b32 m0, s22
	s_nop 0
	global_load_lds_dwordx4 v[208:209], off
	v_lshl_add_u64 v[208:209], v[222:223], 0, s[90:91]
	s_mov_b32 m0, s23
	s_nop 0
	global_load_lds_dwordx4 v[208:209], off
	s_waitcnt vmcnt(8)
	s_waitcnt lgkmcnt(0)
	s_barrier
	s_setprio 0
	s_waitcnt lgkmcnt(0)
	v_mfma_f32_16x16x32_bf16 v[60:63], v[140:143], v[176:179], v[60:63]
	v_mfma_f32_16x16x32_bf16 v[52:55], v[152:155], v[176:179], v[52:55]
	v_mfma_f32_16x16x32_bf16 v[44:47], v[140:143], v[184:187], v[44:47]
	v_mfma_f32_16x16x32_bf16 v[36:39], v[152:155], v[184:187], v[36:39]
	v_mfma_f32_16x16x32_bf16 v[28:31], v[140:143], v[192:195], v[28:31]
	v_mfma_f32_16x16x32_bf16 v[20:23], v[152:155], v[192:195], v[20:23]
	v_mfma_f32_16x16x32_bf16 v[12:15], v[140:143], v[200:203], v[12:15]
	v_mfma_f32_16x16x32_bf16 v[4:7], v[152:155], v[200:203], v[4:7]
	v_mfma_f32_16x16x32_bf16 v[60:63], v[148:151], v[180:183], v[60:63]
	v_mfma_f32_16x16x32_bf16 v[52:55], v[156:159], v[180:183], v[52:55]
	v_mfma_f32_16x16x32_bf16 v[44:47], v[148:151], v[188:191], v[44:47]
	v_mfma_f32_16x16x32_bf16 v[36:39], v[156:159], v[188:191], v[36:39]
	v_mfma_f32_16x16x32_bf16 v[28:31], v[148:151], v[196:199], v[28:31]
	v_mfma_f32_16x16x32_bf16 v[20:23], v[156:159], v[196:199], v[20:23]
	v_mfma_f32_16x16x32_bf16 v[12:15], v[148:151], v[204:207], v[12:15]
	v_mfma_f32_16x16x32_bf16 v[4:7], v[156:159], v[204:207], v[4:7]
	v_mfma_f32_16x16x32_bf16 v[56:59], v[160:163], v[176:179], v[56:59]
	v_mfma_f32_16x16x32_bf16 v[48:51], v[168:171], v[176:179], v[48:51]
	v_mfma_f32_16x16x32_bf16 v[40:43], v[160:163], v[184:187], v[40:43]
	v_mfma_f32_16x16x32_bf16 v[32:35], v[168:171], v[184:187], v[32:35]
	v_mfma_f32_16x16x32_bf16 v[24:27], v[160:163], v[192:195], v[24:27]
	v_mfma_f32_16x16x32_bf16 v[16:19], v[168:171], v[192:195], v[16:19]
	v_mfma_f32_16x16x32_bf16 v[8:11], v[160:163], v[200:203], v[8:11]
	v_mfma_f32_16x16x32_bf16 v[0:3], v[168:171], v[200:203], v[0:3]
	v_mfma_f32_16x16x32_bf16 v[56:59], v[164:167], v[180:183], v[56:59]
	v_mfma_f32_16x16x32_bf16 v[48:51], v[172:175], v[180:183], v[48:51]
	v_mfma_f32_16x16x32_bf16 v[40:43], v[164:167], v[188:191], v[40:43]
	v_mfma_f32_16x16x32_bf16 v[32:35], v[172:175], v[188:191], v[32:35]
	v_mfma_f32_16x16x32_bf16 v[24:27], v[164:167], v[196:199], v[24:27]
	v_mfma_f32_16x16x32_bf16 v[16:19], v[172:175], v[196:199], v[16:19]
	v_mfma_f32_16x16x32_bf16 v[8:11], v[164:167], v[204:207], v[8:11]
	v_mfma_f32_16x16x32_bf16 v[0:3], v[172:175], v[204:207], v[0:3]
	s_barrier
	s_setprio 1
	s_add_i32 s36, s36, 2
	s_add_u32 s66, s66, 0x100
	s_addc_u32 s67, s67, 0
	s_add_u32 s34, s34, 0x100
	s_addc_u32 s35, s35, 0
	s_cmp_gt_u32 s36, 13
	s_cbranch_scc0 .LBB0_813
	s_setprio 0
	s_and_b64 vcc, exec, s[46:47]
	s_cbranch_vccz .LBB0_816
	s_barrier

; #define PG8_STAGE(bufoff, gbase, voff) do { _Pragma("unroll") for (int _i = 0; _i < 2; ++_i) \
;         __builtin_amdgcn_global_load_lds((const unsigned*)((const char*)(gbase) + (voff)[_i]), (PG8_LAS unsigned*)(lds + (bufoff) + ldsw + _i * 8192), 16, 0, 0); } while (0)
; #define PG8_LDA(dst, b, h) do { _Pragma("unroll") for (int m = 0; m < 4; ++m) _Pragma("unroll") for (int k = 0; k < 2; ++k) dst[m][k] = *(const PG8_LAS bf16x8*)(lds + PG8_SA(b, h) + aoff + m * 2048 + k * 1024); } while (0)
; #define PG8_LDB(dst, b, h) do { _Pragma("unroll") for (int n = 0; n < 2; ++n) _Pragma("unroll") for (int k = 0; k < 2; ++k) dst[n][k] = *(const PG8_LAS bf16x8*)(lds + PG8_SB(b, h) + boff + n * 2048 + k * 1024); } while (0)
; #define PG8_MMA(ai, bj, At, Bt) do { __builtin_amdgcn_s_setprio(1); _Pragma("unroll") for (int m = 0; m < 4; ++m) _Pragma("unroll") for (int n = 0; n < 2; ++n) _Pragma("unroll") for (int k = 0; k < 2; ++k) \
;         acc[ai][bj][m][n] = __builtin_amdgcn_mfma_f32_16x16x32_bf16(Bt[n][k], At[m][k], acc[ai][bj][m][n], 0, 0, 0); __builtin_amdgcn_s_setprio(0); } while (0)
; #define PG8_WAIT_V(n) asm volatile("s_waitcnt vmcnt(" #n ")" ::: "memory")
; #define PG8_WAIT_L(n) asm volatile("s_waitcnt lgkmcnt(" #n ")" ::: "memory")
; #define PG8_BAR __builtin_amdgcn_s_barrier()
; #define PG8_SCHED __builtin_amdgcn_sched_barrier(0)
; template <class Epi, class Sched, bool ALIGN_EPI = false, bool SP2 = false>
; __device__ __forceinline__ void gemm_phase(PG8_LAS unsigned char* lds, const Gemm g, const Sched& S, const Epi& E) {
;     ...
;             const bool last = (t == nt - 2);
;             const char* a1 = cA + (size_t)(t + 1) * kstep;
;             const char* a2 = last ? nA : cA + (size_t)(t + 2) * kstep; const char* b2 = last ? nB : cB + (size_t)(t + 2) * kstep;
;             const char* a3 = a2 + kstep; const char* b3 = b2 + kstep;
;             if (last && has_next) S.a_ready(nxt);
;             if constexpr (SP2) {
;             PG8_LDB(B0, 0, 0); PG8_LDB(B1, 0, 1); PG8_SCHED; PG8_LDA(At, 0, 0); PG8_STAGE(PG8_SA(1, 1), a1 + hstep, voffA);
;             PG8_WAIT_V(8); PG8_WAIT_L(0); PG8_BAR; PG8_MMA(0, 0, At, B0); PG8_MMA(0, 1, At, B1); PG8_BAR; PG8_SCHED;
.LBB0_957:
	s_add_u32 s44, s96, 0x100
	s_addc_u32 s45, s97, 0
	s_add_i32 s8, 0, 0x10000
	s_cmp_eq_u32 s70, 40
	s_cselect_b32 s65, s67, s45
	s_cselect_b32 s64, s66, s44
	s_cselect_b32 s47, s73, s37
	s_cselect_b32 s46, s72, s36
	s_add_i32 s88, 0, 0x14000
	v_add_u32_e32 v142, s8, v185
	v_add_u32_e32 v168, s88, v185
	ds_read_b128 v[130:133], v142
	ds_read_b128 v[134:137], v142 offset:1024
	ds_read_b128 v[138:141], v142 offset:2048
	ds_read_b128 v[142:145], v142 offset:3072
	ds_read_b128 v[156:159], v168
	ds_read_b128 v[160:163], v168 offset:1024
	ds_read_b128 v[164:167], v168 offset:2048
	ds_read_b128 v[168:171], v168 offset:3072
	v_lshl_add_u64 v[208:209], s[96:97], 0, v[152:153]
	s_add_i32 m0, s15, 0xc000
	ds_read_b128 v[172:175], v191
	ds_read_b128 v[176:179], v191 offset:1024
	ds_read_b128 v[180:183], v191 offset:2048
	ds_read_b128 v[186:189], v191 offset:3072
	ds_read_b128 v[192:195], v191 offset:4096
	ds_read_b128 v[196:199], v191 offset:5120
	ds_read_b128 v[200:203], v191 offset:6144
	ds_read_b128 v[204:207], v191 offset:7168
	global_load_lds_dwordx4 v[208:209], off
	v_lshl_add_u64 v[208:209], s[96:97], 0, v[154:155]
	s_add_i32 m0, s15, 0xe000
	s_nop 0
	global_load_lds_dwordx4 v[208:209], off
	s_waitcnt vmcnt(8)
	s_waitcnt lgkmcnt(0)
	s_barrier
	s_setprio 0
	s_waitcnt lgkmcnt(0)
	v_mfma_f32_16x16x32_bf16 v[124:127], v[130:133], v[172:175], v[124:127]
	v_mfma_f32_16x16x32_bf16 v[120:123], v[138:141], v[172:175], v[120:123]
	v_mfma_f32_16x16x32_bf16 v[108:111], v[130:133], v[180:183], v[108:111]
	v_mfma_f32_16x16x32_bf16 v[104:107], v[138:141], v[180:183], v[104:107]
	v_mfma_f32_16x16x32_bf16 v[92:95], v[130:133], v[192:195], v[92:95]
	v_mfma_f32_16x16x32_bf16 v[88:91], v[138:141], v[192:195], v[88:91]
	v_mfma_f32_16x16x32_bf16 v[76:79], v[130:133], v[200:203], v[76:79]
	v_mfma_f32_16x16x32_bf16 v[72:75], v[138:141], v[200:203], v[72:75]
	v_mfma_f32_16x16x32_bf16 v[124:127], v[134:137], v[176:179], v[124:127]
	v_mfma_f32_16x16x32_bf16 v[120:123], v[142:145], v[176:179], v[120:123]
	v_mfma_f32_16x16x32_bf16 v[108:111], v[134:137], v[186:189], v[108:111]
	v_mfma_f32_16x16x32_bf16 v[104:107], v[142:145], v[186:189], v[104:107]
	v_mfma_f32_16x16x32_bf16 v[92:95], v[134:137], v[196:199], v[92:95]
	v_mfma_f32_16x16x32_bf16 v[88:91], v[142:145], v[196:199], v[88:91]
	v_mfma_f32_16x16x32_bf16 v[76:79], v[134:137], v[204:207], v[76:79]
	v_mfma_f32_16x16x32_bf16 v[72:75], v[142:145], v[204:207], v[72:75]
	v_mfma_f32_16x16x32_bf16 v[116:119], v[156:159], v[172:175], v[116:119]
	v_mfma_f32_16x16x32_bf16 v[112:115], v[164:167], v[172:175], v[112:115]
	v_mfma_f32_16x16x32_bf16 v[100:103], v[156:159], v[180:183], v[100:103]
	v_mfma_f32_16x16x32_bf16 v[96:99], v[164:167], v[180:183], v[96:99]
	v_mfma_f32_16x16x32_bf16 v[84:87], v[156:159], v[192:195], v[84:87]
	v_mfma_f32_16x16x32_bf16 v[80:83], v[164:167], v[192:195], v[80:83]
	v_mfma_f32_16x16x32_bf16 v[68:71], v[156:159], v[200:203], v[68:71]
	v_mfma_f32_16x16x32_bf16 v[64:67], v[164:167], v[200:203], v[64:67]
	v_mfma_f32_16x16x32_bf16 v[116:119], v[160:163], v[176:179], v[116:119]
	v_mfma_f32_16x16x32_bf16 v[112:115], v[168:171], v[176:179], v[112:115]
	v_mfma_f32_16x16x32_bf16 v[100:103], v[160:163], v[186:189], v[100:103]
	v_mfma_f32_16x16x32_bf16 v[96:99], v[168:171], v[186:189], v[96:99]
	v_mfma_f32_16x16x32_bf16 v[84:87], v[160:163], v[196:199], v[84:87]
	v_mfma_f32_16x16x32_bf16 v[80:83], v[168:171], v[196:199], v[80:83]
	v_mfma_f32_16x16x32_bf16 v[68:71], v[160:163], v[204:207], v[68:71]
	v_mfma_f32_16x16x32_bf16 v[64:67], v[168:171], v[204:207], v[64:67]
	s_barrier
	s_setprio 1
	s_add_i32 s8, s8, s14
	v_lshl_add_u64 v[208:209], s[46:47], 0, v[128:129]
	s_mov_b32 m0, s8
	ds_read_b128 v[172:175], v191 offset:16384
	ds_read_b128 v[176:179], v191 offset:17408
	ds_read_b128 v[180:183], v191 offset:18432
	ds_read_b128 v[186:189], v191 offset:19456
	ds_read_b128 v[192:195], v191 offset:20480
	ds_read_b128 v[196:199], v191 offset:21504
	ds_read_b128 v[200:203], v191 offset:22528
	ds_read_b128 v[204:207], v191 offset:23552
	global_load_lds_dwordx4 v[208:209], off
	s_add_i32 m0, s8, 0x2000
	s_add_u32 s84, s46, 0xb0000
	v_lshl_add_u64 v[210:211], s[46:47], 0, v[146:147]
	s_addc_u32 s85, s47, 0
	s_add_i32 s8, s88, s14
	global_load_lds_dwordx4 v[210:211], off
	v_lshl_add_u64 v[214:215], s[84:85], 0, v[128:129]
	s_mov_b32 m0, s8
	v_lshl_add_u64 v[222:223], s[64:65], 0, v[148:149]
	global_load_lds_dwordx4 v[214:215], off
	v_lshl_add_u64 v[214:215], s[84:85], 0, v[146:147]
	s_add_i32 m0, s8, 0x2000
	s_nop 0
	global_load_lds_dwordx4 v[214:215], off
	v_lshl_add_u64 v[214:215], s[64:65], 0, v[150:151]
	s_mov_b32 m0, s15
	s_nop 0
	global_load_lds_dwordx4 v[214:215], off
	s_mov_b32 m0, s18
	s_nop 0
	global_load_lds_dwordx4 v[222:223], off
	s_waitcnt vmcnt(8)
	s_waitcnt lgkmcnt(0)
	s_barrier
; #define PG8_STAGE(bufoff, gbase, voff) do { _Pragma("unroll") for (int _i = 0; _i < 2; ++_i) \
;         __builtin_amdgcn_global_load_lds((const unsigned*)((const char*)(gbase) + (voff)[_i]), (PG8_LAS unsigned*)(lds + (bufoff) + ldsw + _i * 8192), 16, 0, 0); } while (0)
; #define PG8_LDA(dst, b, h) do { _Pragma("unroll") for (int m = 0; m < 4; ++m) _Pragma("unroll") for (int k = 0; k < 2; ++k) dst[m][k] = *(const PG8_LAS bf16x8*)(lds + PG8_SA(b, h) + aoff + m * 2048 + k * 1024); } while (0)
; #define PG8_LDB(dst, b, h) do { _Pragma("unroll") for (int n = 0; n < 2; ++n) _Pragma("unroll") for (int k = 0; k < 2; ++k) dst[n][k] = *(const PG8_LAS bf16x8*)(lds + PG8_SB(b, h) + boff + n * 2048 + k * 1024); } while (0)
; #define PG8_MMA(ai, bj, At, Bt) do { __builtin_amdgcn_s_setprio(1); _Pragma("unroll") for (int m = 0; m < 4; ++m) _Pragma("unroll") for (int n = 0; n < 2; ++n) _Pragma("unroll") for (int k = 0; k < 2; ++k) \
;         acc[ai][bj][m][n] = __builtin_amdgcn_mfma_f32_16x16x32_bf16(Bt[n][k], At[m][k], acc[ai][bj][m][n], 0, 0, 0); __builtin_amdgcn_s_setprio(0); } while (0)
; #define PG8_WAIT_V(n) asm volatile("s_waitcnt vmcnt(" #n ")" ::: "memory")
; template <class Epi, class Sched, bool ALIGN_EPI = false, bool SP2 = false>
; __device__ __forceinline__ void gemm_phase(PG8_LAS unsigned char* lds, const Gemm g, const Sched& S, const Epi& E) {
;     ...
;             PG8_LDB(B0, 0, 0); PG8_LDB(B1, 0, 1); PG8_SCHED; PG8_LDA(At, 0, 0); PG8_STAGE(PG8_SA(1, 1), a1 + hstep, voffA);
;             PG8_WAIT_V(8); PG8_WAIT_L(0); PG8_BAR; PG8_MMA(0, 0, At, B0); PG8_MMA(0, 1, At, B1); PG8_BAR; PG8_SCHED;
;             PG8_LDA(At, 0, 1); PG8_STAGE(PG8_SB(0, 0), b2, voffB); PG8_STAGE(PG8_SB(0, 1), b2 + hstep, voffB); PG8_STAGE(PG8_SA(0, 0), a2, voffA);
;             PG8_WAIT_V(8); PG8_WAIT_L(0); PG8_BAR; PG8_MMA(1, 0, At, B0); PG8_MMA(1, 1, At, B1); PG8_BAR; PG8_SCHED;
;             PG8_LDB(B0, 1, 0); PG8_LDB(B1, 1, 1); PG8_SCHED; PG8_LDA(At, 1, 0); PG8_STAGE(PG8_SA(0, 1), a2 + hstep, voffA);
;             PG8_WAIT_V(8); PG8_WAIT_L(0); PG8_BAR; PG8_MMA(0, 0, At, B0); PG8_MMA(0, 1, At, B1); PG8_BAR; PG8_SCHED;
;             PG8_LDA(At, 1, 1); PG8_STAGE(PG8_SB(1, 0), b3, voffB); PG8_STAGE(PG8_SB(1, 1), b3 + hstep, voffB); PG8_STAGE(PG8_SA(1, 0), a3, voffA);
;             PG8_WAIT_V(8); PG8_WAIT_L(0); PG8_BAR; PG8_MMA(1, 0, At, B0); PG8_MMA(1, 1, At, B1); PG8_BAR; PG8_SCHED;
	s_setprio 0
	s_waitcnt lgkmcnt(0)
	v_mfma_f32_16x16x32_bf16 v[60:63], v[130:133], v[172:175], v[60:63]
	v_mfma_f32_16x16x32_bf16 v[56:59], v[138:141], v[172:175], v[56:59]
	v_mfma_f32_16x16x32_bf16 v[44:47], v[130:133], v[180:183], v[44:47]
	v_mfma_f32_16x16x32_bf16 v[40:43], v[138:141], v[180:183], v[40:43]
	v_mfma_f32_16x16x32_bf16 v[28:31], v[130:133], v[192:195], v[28:31]
	v_mfma_f32_16x16x32_bf16 v[24:27], v[138:141], v[192:195], v[24:27]
	v_mfma_f32_16x16x32_bf16 v[12:15], v[130:133], v[200:203], v[12:15]
	v_mfma_f32_16x16x32_bf16 v[8:11], v[138:141], v[200:203], v[8:11]
	v_mfma_f32_16x16x32_bf16 v[60:63], v[134:137], v[176:179], v[60:63]
	v_mfma_f32_16x16x32_bf16 v[56:59], v[142:145], v[176:179], v[56:59]
	v_mfma_f32_16x16x32_bf16 v[44:47], v[134:137], v[186:189], v[44:47]
	v_mfma_f32_16x16x32_bf16 v[40:43], v[142:145], v[186:189], v[40:43]
	v_mfma_f32_16x16x32_bf16 v[28:31], v[134:137], v[196:199], v[28:31]
	v_mfma_f32_16x16x32_bf16 v[24:27], v[142:145], v[196:199], v[24:27]
	v_mfma_f32_16x16x32_bf16 v[12:15], v[134:137], v[204:207], v[12:15]
	v_mfma_f32_16x16x32_bf16 v[8:11], v[142:145], v[204:207], v[8:11]
	v_mfma_f32_16x16x32_bf16 v[52:55], v[156:159], v[172:175], v[52:55]
	v_mfma_f32_16x16x32_bf16 v[48:51], v[164:167], v[172:175], v[48:51]
	v_mfma_f32_16x16x32_bf16 v[36:39], v[156:159], v[180:183], v[36:39]
	v_mfma_f32_16x16x32_bf16 v[32:35], v[164:167], v[180:183], v[32:35]
	v_mfma_f32_16x16x32_bf16 v[20:23], v[156:159], v[192:195], v[20:23]
	v_mfma_f32_16x16x32_bf16 v[16:19], v[164:167], v[192:195], v[16:19]
	v_mfma_f32_16x16x32_bf16 v[4:7], v[156:159], v[200:203], v[4:7]
	v_mfma_f32_16x16x32_bf16 v[0:3], v[164:167], v[200:203], v[0:3]
	v_mfma_f32_16x16x32_bf16 v[52:55], v[160:163], v[176:179], v[52:55]
	v_mfma_f32_16x16x32_bf16 v[48:51], v[168:171], v[176:179], v[48:51]
	v_mfma_f32_16x16x32_bf16 v[36:39], v[160:163], v[186:189], v[36:39]
	v_mfma_f32_16x16x32_bf16 v[32:35], v[168:171], v[186:189], v[32:35]
	v_mfma_f32_16x16x32_bf16 v[20:23], v[160:163], v[196:199], v[20:23]
	v_mfma_f32_16x16x32_bf16 v[16:19], v[168:171], v[196:199], v[16:19]
	v_mfma_f32_16x16x32_bf16 v[4:7], v[160:163], v[204:207], v[4:7]
	v_mfma_f32_16x16x32_bf16 v[0:3], v[168:171], v[204:207], v[0:3]
	s_barrier
	s_setprio 1
	s_add_i32 s8, 0, 0x18000
	s_add_i32 s84, 0, 0x1c000
	v_add_u32_e32 v142, s8, v185
	v_add_u32_e32 v168, s84, v185
	ds_read_b128 v[130:133], v142
	ds_read_b128 v[134:137], v142 offset:1024
	ds_read_b128 v[138:141], v142 offset:2048
	ds_read_b128 v[142:145], v142 offset:3072
	ds_read_b128 v[156:159], v168
	ds_read_b128 v[160:163], v168 offset:1024
	ds_read_b128 v[164:167], v168 offset:2048
	ds_read_b128 v[168:171], v168 offset:3072
	s_add_u32 s64, s64, 0xb0000
	s_addc_u32 s65, s65, 0
	s_mov_b32 m0, s19
	v_lshl_add_u64 v[228:229], s[64:65], 0, v[150:151]
	ds_read_b128 v[172:175], v191 offset:32768
	ds_read_b128 v[176:179], v191 offset:33792
	ds_read_b128 v[180:183], v191 offset:34816
	ds_read_b128 v[186:189], v191 offset:35840
	ds_read_b128 v[192:195], v191 offset:36864
	ds_read_b128 v[196:199], v191 offset:37888
	ds_read_b128 v[200:203], v191 offset:38912
	ds_read_b128 v[204:207], v191 offset:39936
	global_load_lds_dwordx4 v[228:229], off
	v_lshl_add_u64 v[228:229], s[64:65], 0, v[148:149]
	s_mov_b32 m0, s20
	s_nop 0
	global_load_lds_dwordx4 v[228:229], off
	s_waitcnt vmcnt(8)
	s_waitcnt lgkmcnt(0)
	s_barrier
	s_setprio 0
	s_waitcnt lgkmcnt(0)
	v_mfma_f32_16x16x32_bf16 v[124:127], v[130:133], v[172:175], v[124:127]
	v_mfma_f32_16x16x32_bf16 v[120:123], v[138:141], v[172:175], v[120:123]
	v_mfma_f32_16x16x32_bf16 v[108:111], v[130:133], v[180:183], v[108:111]
	v_mfma_f32_16x16x32_bf16 v[104:107], v[138:141], v[180:183], v[104:107]
	v_mfma_f32_16x16x32_bf16 v[92:95], v[130:133], v[192:195], v[92:95]
	v_mfma_f32_16x16x32_bf16 v[88:91], v[138:141], v[192:195], v[88:91]
	v_mfma_f32_16x16x32_bf16 v[76:79], v[130:133], v[200:203], v[76:79]
	v_mfma_f32_16x16x32_bf16 v[72:75], v[138:141], v[200:203], v[72:75]
	v_mfma_f32_16x16x32_bf16 v[124:127], v[134:137], v[176:179], v[124:127]
	v_mfma_f32_16x16x32_bf16 v[120:123], v[142:145], v[176:179], v[120:123]
	v_mfma_f32_16x16x32_bf16 v[108:111], v[134:137], v[186:189], v[108:111]
	v_mfma_f32_16x16x32_bf16 v[104:107], v[142:145], v[186:189], v[104:107]
	v_mfma_f32_16x16x32_bf16 v[92:95], v[134:137], v[196:199], v[92:95]
	v_mfma_f32_16x16x32_bf16 v[88:91], v[142:145], v[196:199], v[88:91]
	v_mfma_f32_16x16x32_bf16 v[76:79], v[134:137], v[204:207], v[76:79]
	v_mfma_f32_16x16x32_bf16 v[72:75], v[142:145], v[204:207], v[72:75]
	v_mfma_f32_16x16x32_bf16 v[116:119], v[156:159], v[172:175], v[116:119]
	v_mfma_f32_16x16x32_bf16 v[112:115], v[164:167], v[172:175], v[112:115]
	v_mfma_f32_16x16x32_bf16 v[100:103], v[156:159], v[180:183], v[100:103]
	v_mfma_f32_16x16x32_bf16 v[96:99], v[164:167], v[180:183], v[96:99]
	v_mfma_f32_16x16x32_bf16 v[84:87], v[156:159], v[192:195], v[84:87]
	v_mfma_f32_16x16x32_bf16 v[80:83], v[164:167], v[192:195], v[80:83]
	v_mfma_f32_16x16x32_bf16 v[68:71], v[156:159], v[200:203], v[68:71]
	v_mfma_f32_16x16x32_bf16 v[64:67], v[164:167], v[200:203], v[64:67]
	v_mfma_f32_16x16x32_bf16 v[116:119], v[160:163], v[176:179], v[116:119]
	v_mfma_f32_16x16x32_bf16 v[112:115], v[168:171], v[176:179], v[112:115]
	v_mfma_f32_16x16x32_bf16 v[100:103], v[160:163], v[186:189], v[100:103]
	v_mfma_f32_16x16x32_bf16 v[96:99], v[168:171], v[186:189], v[96:99]
	v_mfma_f32_16x16x32_bf16 v[84:87], v[160:163], v[196:199], v[84:87]
	v_mfma_f32_16x16x32_bf16 v[80:83], v[168:171], v[196:199], v[80:83]
	v_mfma_f32_16x16x32_bf16 v[68:71], v[160:163], v[204:207], v[68:71]
	v_mfma_f32_16x16x32_bf16 v[64:67], v[168:171], v[204:207], v[64:67]
	s_barrier
; #define PG8_STAGE(bufoff, gbase, voff) do { _Pragma("unroll") for (int _i = 0; _i < 2; ++_i) \
;         __builtin_amdgcn_global_load_lds((const unsigned*)((const char*)(gbase) + (voff)[_i]), (PG8_LAS unsigned*)(lds + (bufoff) + ldsw + _i * 8192), 16, 0, 0); } while (0)
; #define PG8_LDA(dst, b, h) do { _Pragma("unroll") for (int m = 0; m < 4; ++m) _Pragma("unroll") for (int k = 0; k < 2; ++k) dst[m][k] = *(const PG8_LAS bf16x8*)(lds + PG8_SA(b, h) + aoff + m * 2048 + k * 1024); } while (0)
; #define PG8_LDB(dst, b, h) do { _Pragma("unroll") for (int n = 0; n < 2; ++n) _Pragma("unroll") for (int k = 0; k < 2; ++k) dst[n][k] = *(const PG8_LAS bf16x8*)(lds + PG8_SB(b, h) + boff + n * 2048 + k * 1024); } while (0)
; #define PG8_MMA(ai, bj, At, Bt) do { __builtin_amdgcn_s_setprio(1); _Pragma("unroll") for (int m = 0; m < 4; ++m) _Pragma("unroll") for (int n = 0; n < 2; ++n) _Pragma("unroll") for (int k = 0; k < 2; ++k) \
;         acc[ai][bj][m][n] = __builtin_amdgcn_mfma_f32_16x16x32_bf16(Bt[n][k], At[m][k], acc[ai][bj][m][n], 0, 0, 0); __builtin_amdgcn_s_setprio(0); } while (0)
; template <class Epi, class Sched, bool ALIGN_EPI = false, bool SP2 = false>
; __device__ __forceinline__ void gemm_phase(PG8_LAS unsigned char* lds, const Gemm g, const Sched& S, const Epi& E) {
;     ...
;             PG8_LDB(B0, 0, 0); PG8_LDB(B1, 0, 1); PG8_SCHED; PG8_LDA(At, 0, 0); PG8_STAGE(PG8_SA(1, 1), a1 + hstep, voffA);
;             PG8_WAIT_V(8); PG8_WAIT_L(0); PG8_BAR; PG8_MMA(0, 0, At, B0); PG8_MMA(0, 1, At, B1); PG8_BAR; PG8_SCHED;
;             PG8_LDA(At, 0, 1); PG8_STAGE(PG8_SB(0, 0), b2, voffB); PG8_STAGE(PG8_SB(0, 1), b2 + hstep, voffB); PG8_STAGE(PG8_SA(0, 0), a2, voffA);
;             PG8_WAIT_V(8); PG8_WAIT_L(0); PG8_BAR; PG8_MMA(1, 0, At, B0); PG8_MMA(1, 1, At, B1); PG8_BAR; PG8_SCHED;
;             PG8_LDB(B0, 1, 0); PG8_LDB(B1, 1, 1); PG8_SCHED; PG8_LDA(At, 1, 0); PG8_STAGE(PG8_SA(0, 1), a2 + hstep, voffA);
;             PG8_WAIT_V(8); PG8_WAIT_L(0); PG8_BAR; PG8_MMA(0, 0, At, B0); PG8_MMA(0, 1, At, B1); PG8_BAR; PG8_SCHED;
;             PG8_LDA(At, 1, 1); PG8_STAGE(PG8_SB(1, 0), b3, voffB); PG8_STAGE(PG8_SB(1, 1), b3 + hstep, voffB); PG8_STAGE(PG8_SA(1, 0), a3, voffA);
;             PG8_WAIT_V(8); PG8_WAIT_L(0); PG8_BAR; PG8_MMA(1, 0, At, B0); PG8_MMA(1, 1, At, B1); PG8_BAR; PG8_SCHED;
;     ...
;         if constexpr (ALIGN_EPI) { if (wr == 0) PG8_BAR; }
	s_setprio 1
	s_add_i32 s8, s8, s14
	v_lshl_add_u64 v[208:209], v[208:209], 0, s[90:91]
	s_mov_b32 m0, s8
	ds_read_b128 v[172:175], v191 offset:49152
	ds_read_b128 v[176:179], v191 offset:50176
	ds_read_b128 v[180:183], v191 offset:51200
	ds_read_b128 v[186:189], v191 offset:52224
	ds_read_b128 v[192:195], v191 offset:53248
	ds_read_b128 v[196:199], v191 offset:54272
	ds_read_b128 v[200:203], v191 offset:55296
	ds_read_b128 v[204:207], v191 offset:56320
	global_load_lds_dwordx4 v[208:209], off
	s_add_i32 m0, s8, 0x2000
	s_add_u32 s46, s46, 0xb0080
	v_lshl_add_u64 v[208:209], v[210:211], 0, s[90:91]
	s_addc_u32 s47, s47, 0
	s_add_i32 s8, s84, s14
	global_load_lds_dwordx4 v[208:209], off
	v_lshl_add_u64 v[208:209], s[46:47], 0, v[128:129]
	s_mov_b32 m0, s8
	s_nop 0
	global_load_lds_dwordx4 v[208:209], off
	v_lshl_add_u64 v[208:209], s[46:47], 0, v[146:147]
	s_add_i32 m0, s8, 0x2000
	s_nop 0
	global_load_lds_dwordx4 v[208:209], off
	v_lshl_add_u64 v[208:209], v[214:215], 0, s[90:91]
	s_mov_b32 m0, s27
	s_nop 0
	global_load_lds_dwordx4 v[208:209], off
	v_lshl_add_u64 v[208:209], v[222:223], 0, s[90:91]
	s_mov_b32 m0, s28
	s_nop 0
	global_load_lds_dwordx4 v[208:209], off
	s_waitcnt vmcnt(8)
	s_waitcnt lgkmcnt(0)
	s_barrier
	s_setprio 0
	s_waitcnt lgkmcnt(0)
	v_mfma_f32_16x16x32_bf16 v[60:63], v[130:133], v[172:175], v[60:63]
	v_mfma_f32_16x16x32_bf16 v[56:59], v[138:141], v[172:175], v[56:59]
	v_mfma_f32_16x16x32_bf16 v[44:47], v[130:133], v[180:183], v[44:47]
	v_mfma_f32_16x16x32_bf16 v[40:43], v[138:141], v[180:183], v[40:43]
	v_mfma_f32_16x16x32_bf16 v[28:31], v[130:133], v[192:195], v[28:31]
	v_mfma_f32_16x16x32_bf16 v[24:27], v[138:141], v[192:195], v[24:27]
	v_mfma_f32_16x16x32_bf16 v[12:15], v[130:133], v[200:203], v[12:15]
	v_mfma_f32_16x16x32_bf16 v[8:11], v[138:141], v[200:203], v[8:11]
	v_mfma_f32_16x16x32_bf16 v[60:63], v[134:137], v[176:179], v[60:63]
	v_mfma_f32_16x16x32_bf16 v[56:59], v[142:145], v[176:179], v[56:59]
	v_mfma_f32_16x16x32_bf16 v[44:47], v[134:137], v[186:189], v[44:47]
	v_mfma_f32_16x16x32_bf16 v[40:43], v[142:145], v[186:189], v[40:43]
	v_mfma_f32_16x16x32_bf16 v[28:31], v[134:137], v[196:199], v[28:31]
	v_mfma_f32_16x16x32_bf16 v[24:27], v[142:145], v[196:199], v[24:27]
	v_mfma_f32_16x16x32_bf16 v[12:15], v[134:137], v[204:207], v[12:15]
	v_mfma_f32_16x16x32_bf16 v[8:11], v[142:145], v[204:207], v[8:11]
	v_mfma_f32_16x16x32_bf16 v[52:55], v[156:159], v[172:175], v[52:55]
	v_mfma_f32_16x16x32_bf16 v[48:51], v[164:167], v[172:175], v[48:51]
	v_mfma_f32_16x16x32_bf16 v[36:39], v[156:159], v[180:183], v[36:39]
	v_mfma_f32_16x16x32_bf16 v[32:35], v[164:167], v[180:183], v[32:35]
	v_mfma_f32_16x16x32_bf16 v[20:23], v[156:159], v[192:195], v[20:23]
	v_mfma_f32_16x16x32_bf16 v[16:19], v[164:167], v[192:195], v[16:19]
	v_mfma_f32_16x16x32_bf16 v[4:7], v[156:159], v[200:203], v[4:7]
	v_mfma_f32_16x16x32_bf16 v[0:3], v[164:167], v[200:203], v[0:3]
	v_mfma_f32_16x16x32_bf16 v[52:55], v[160:163], v[176:179], v[52:55]
	v_mfma_f32_16x16x32_bf16 v[48:51], v[168:171], v[176:179], v[48:51]
	v_mfma_f32_16x16x32_bf16 v[36:39], v[160:163], v[186:189], v[36:39]
	v_mfma_f32_16x16x32_bf16 v[32:35], v[168:171], v[186:189], v[32:35]
	v_mfma_f32_16x16x32_bf16 v[20:23], v[160:163], v[196:199], v[20:23]
	v_mfma_f32_16x16x32_bf16 v[16:19], v[168:171], v[196:199], v[16:19]
	v_mfma_f32_16x16x32_bf16 v[4:7], v[160:163], v[204:207], v[4:7]
	v_mfma_f32_16x16x32_bf16 v[0:3], v[168:171], v[204:207], v[0:3]
	s_barrier
	s_setprio 1
	s_add_i32 s70, s70, 2
	s_add_u32 s36, s36, 0x100
	s_addc_u32 s37, s37, 0
	s_cmp_gt_u32 s70, 41
	s_mov_b64 s[96:97], s[44:45]
	s_cbranch_scc0 .LBB0_957
	s_setprio 0
	s_and_b64 vcc, exec, s[58:59]
	s_cbranch_vccz .LBB0_960
	s_barrier

; #define PG8_STAGE(bufoff, gbase, voff) do { _Pragma("unroll") for (int _i = 0; _i < 2; ++_i) \
;         __builtin_amdgcn_global_load_lds((const unsigned*)((const char*)(gbase) + (voff)[_i]), (PG8_LAS unsigned*)(lds + (bufoff) + ldsw + _i * 8192), 16, 0, 0); } while (0)
; #define PG8_LDA(dst, b, h) do { _Pragma("unroll") for (int m = 0; m < 4; ++m) _Pragma("unroll") for (int k = 0; k < 2; ++k) dst[m][k] = *(const PG8_LAS bf16x8*)(lds + PG8_SA(b, h) + aoff + m * 2048 + k * 1024); } while (0)
; #define PG8_LDB(dst, b, h) do { _Pragma("unroll") for (int n = 0; n < 2; ++n) _Pragma("unroll") for (int k = 0; k < 2; ++k) dst[n][k] = *(const PG8_LAS bf16x8*)(lds + PG8_SB(b, h) + boff + n * 2048 + k * 1024); } while (0)
; #define PG8_MMA(ai, bj, At, Bt) do { __builtin_amdgcn_s_setprio(1); _Pragma("unroll") for (int m = 0; m < 4; ++m) _Pragma("unroll") for (int n = 0; n < 2; ++n) _Pragma("unroll") for (int k = 0; k < 2; ++k) \
;         acc[ai][bj][m][n] = __builtin_amdgcn_mfma_f32_16x16x32_bf16(Bt[n][k], At[m][k], acc[ai][bj][m][n], 0, 0, 0); __builtin_amdgcn_s_setprio(0); } while (0)
; #define PG8_WAIT_V(n) asm volatile("s_waitcnt vmcnt(" #n ")" ::: "memory")
; #define PG8_WAIT_L(n) asm volatile("s_waitcnt lgkmcnt(" #n ")" ::: "memory")
; #define PG8_BAR __builtin_amdgcn_s_barrier()
; #define PG8_SCHED __builtin_amdgcn_sched_barrier(0)
; template <class Epi, class Sched, bool ALIGN_EPI = false, bool SP2 = false>
; __device__ __forceinline__ void gemm_phase(PG8_LAS unsigned char* lds, const Gemm g, const Sched& S, const Epi& E) {
;     ...
;             const bool last = (t == nt - 2);
;             const char* a1 = cA + (size_t)(t + 1) * kstep;
;             const char* a2 = last ? nA : cA + (size_t)(t + 2) * kstep; const char* b2 = last ? nB : cB + (size_t)(t + 2) * kstep;
;             const char* a3 = a2 + kstep; const char* b3 = b2 + kstep;
;             if (last && has_next) S.a_ready(nxt);
;             if constexpr (SP2) {
;             PG8_LDB(B0, 0, 0); PG8_LDB(B1, 0, 1); PG8_SCHED; PG8_LDA(At, 0, 0); PG8_STAGE(PG8_SA(1, 1), a1 + hstep, voffA);
;             PG8_WAIT_V(8); PG8_WAIT_L(0); PG8_BAR; PG8_MMA(0, 0, At, B0); PG8_MMA(0, 1, At, B1); PG8_BAR; PG8_SCHED;
.LBB0_995:
	s_add_u32 s42, s96, 0x100
	s_addc_u32 s43, s97, 0
	s_add_i32 s8, 0, 0x10000
	s_cmp_eq_u32 s84, 40
	s_cselect_b32 s65, s67, s43
	s_cselect_b32 s64, s66, s42
	s_cselect_b32 s47, s73, s37
	s_cselect_b32 s46, s72, s36
	s_add_i32 s85, 0, 0x14000
	v_add_u32_e32 v142, s8, v201
	v_add_u32_e32 v168, s85, v201
	ds_read_b128 v[130:133], v142
	ds_read_b128 v[134:137], v142 offset:1024
	ds_read_b128 v[138:141], v142 offset:2048
	ds_read_b128 v[142:145], v142 offset:3072
	ds_read_b128 v[156:159], v168
	ds_read_b128 v[160:163], v168 offset:1024
	ds_read_b128 v[164:167], v168 offset:2048
	ds_read_b128 v[168:171], v168 offset:3072
	v_lshl_add_u64 v[208:209], s[96:97], 0, v[152:153]
	s_add_i32 m0, s15, 0xc000
	ds_read_b128 v[172:175], v203
	ds_read_b128 v[176:179], v203 offset:1024
	ds_read_b128 v[180:183], v203 offset:2048
	ds_read_b128 v[184:187], v203 offset:3072
	ds_read_b128 v[188:191], v203 offset:4096
	ds_read_b128 v[192:195], v203 offset:5120
	ds_read_b128 v[196:199], v203 offset:6144
	ds_read_b128 v[204:207], v203 offset:7168
	global_load_lds_dwordx4 v[208:209], off
	v_lshl_add_u64 v[208:209], s[96:97], 0, v[154:155]
	s_add_i32 m0, s15, 0xe000
	s_nop 0
	global_load_lds_dwordx4 v[208:209], off
	s_waitcnt vmcnt(8)
	s_waitcnt lgkmcnt(0)
	s_barrier
	s_setprio 0
	s_waitcnt lgkmcnt(0)
	v_mfma_f32_16x16x32_bf16 v[124:127], v[130:133], v[172:175], v[124:127]
	v_mfma_f32_16x16x32_bf16 v[120:123], v[138:141], v[172:175], v[120:123]
	v_mfma_f32_16x16x32_bf16 v[108:111], v[130:133], v[180:183], v[108:111]
	v_mfma_f32_16x16x32_bf16 v[104:107], v[138:141], v[180:183], v[104:107]
	v_mfma_f32_16x16x32_bf16 v[92:95], v[130:133], v[188:191], v[92:95]
	v_mfma_f32_16x16x32_bf16 v[88:91], v[138:141], v[188:191], v[88:91]
	v_mfma_f32_16x16x32_bf16 v[76:79], v[130:133], v[196:199], v[76:79]
	v_mfma_f32_16x16x32_bf16 v[72:75], v[138:141], v[196:199], v[72:75]
	v_mfma_f32_16x16x32_bf16 v[124:127], v[134:137], v[176:179], v[124:127]
	v_mfma_f32_16x16x32_bf16 v[120:123], v[142:145], v[176:179], v[120:123]
	v_mfma_f32_16x16x32_bf16 v[108:111], v[134:137], v[184:187], v[108:111]
	v_mfma_f32_16x16x32_bf16 v[104:107], v[142:145], v[184:187], v[104:107]
	v_mfma_f32_16x16x32_bf16 v[92:95], v[134:137], v[192:195], v[92:95]
	v_mfma_f32_16x16x32_bf16 v[88:91], v[142:145], v[192:195], v[88:91]
	v_mfma_f32_16x16x32_bf16 v[76:79], v[134:137], v[204:207], v[76:79]
	v_mfma_f32_16x16x32_bf16 v[72:75], v[142:145], v[204:207], v[72:75]
	v_mfma_f32_16x16x32_bf16 v[116:119], v[156:159], v[172:175], v[116:119]
	v_mfma_f32_16x16x32_bf16 v[112:115], v[164:167], v[172:175], v[112:115]
	v_mfma_f32_16x16x32_bf16 v[100:103], v[156:159], v[180:183], v[100:103]
	v_mfma_f32_16x16x32_bf16 v[96:99], v[164:167], v[180:183], v[96:99]
	v_mfma_f32_16x16x32_bf16 v[84:87], v[156:159], v[188:191], v[84:87]
	v_mfma_f32_16x16x32_bf16 v[80:83], v[164:167], v[188:191], v[80:83]
	v_mfma_f32_16x16x32_bf16 v[68:71], v[156:159], v[196:199], v[68:71]
	v_mfma_f32_16x16x32_bf16 v[64:67], v[164:167], v[196:199], v[64:67]
	v_mfma_f32_16x16x32_bf16 v[116:119], v[160:163], v[176:179], v[116:119]
	v_mfma_f32_16x16x32_bf16 v[112:115], v[168:171], v[176:179], v[112:115]
	v_mfma_f32_16x16x32_bf16 v[100:103], v[160:163], v[184:187], v[100:103]
	v_mfma_f32_16x16x32_bf16 v[96:99], v[168:171], v[184:187], v[96:99]
	v_mfma_f32_16x16x32_bf16 v[84:87], v[160:163], v[192:195], v[84:87]
	v_mfma_f32_16x16x32_bf16 v[80:83], v[168:171], v[192:195], v[80:83]
	v_mfma_f32_16x16x32_bf16 v[68:71], v[160:163], v[204:207], v[68:71]
	v_mfma_f32_16x16x32_bf16 v[64:67], v[168:171], v[204:207], v[64:67]
	s_barrier
	s_setprio 1
	s_add_i32 s8, s8, s14
	v_lshl_add_u64 v[208:209], s[46:47], 0, v[128:129]
	s_mov_b32 m0, s8
	ds_read_b128 v[172:175], v203 offset:16384
	ds_read_b128 v[176:179], v203 offset:17408
	ds_read_b128 v[180:183], v203 offset:18432
	ds_read_b128 v[184:187], v203 offset:19456
	ds_read_b128 v[188:191], v203 offset:20480
	ds_read_b128 v[192:195], v203 offset:21504
	ds_read_b128 v[196:199], v203 offset:22528
	ds_read_b128 v[204:207], v203 offset:23552
	global_load_lds_dwordx4 v[208:209], off
	s_add_i32 m0, s8, 0x2000
	s_add_u32 s96, s46, 0xb0000
	v_lshl_add_u64 v[210:211], s[46:47], 0, v[146:147]
	s_addc_u32 s97, s47, 0
	s_add_i32 s8, s85, s14
	global_load_lds_dwordx4 v[210:211], off
	v_lshl_add_u64 v[214:215], s[96:97], 0, v[128:129]
	s_mov_b32 m0, s8
	v_lshl_add_u64 v[222:223], s[64:65], 0, v[148:149]
	global_load_lds_dwordx4 v[214:215], off
	v_lshl_add_u64 v[214:215], s[96:97], 0, v[146:147]
	s_add_i32 m0, s8, 0x2000
	s_nop 0
	global_load_lds_dwordx4 v[214:215], off
	v_lshl_add_u64 v[214:215], s[64:65], 0, v[150:151]
	s_mov_b32 m0, s15
	s_nop 0
	global_load_lds_dwordx4 v[214:215], off
	s_mov_b32 m0, s18
	s_nop 0
	global_load_lds_dwordx4 v[222:223], off
	s_waitcnt vmcnt(8)
	s_waitcnt lgkmcnt(0)
	s_barrier
; #define PG8_STAGE(bufoff, gbase, voff) do { _Pragma("unroll") for (int _i = 0; _i < 2; ++_i) \
;         __builtin_amdgcn_global_load_lds((const unsigned*)((const char*)(gbase) + (voff)[_i]), (PG8_LAS unsigned*)(lds + (bufoff) + ldsw + _i * 8192), 16, 0, 0); } while (0)
; #define PG8_LDA(dst, b, h) do { _Pragma("unroll") for (int m = 0; m < 4; ++m) _Pragma("unroll") for (int k = 0; k < 2; ++k) dst[m][k] = *(const PG8_LAS bf16x8*)(lds + PG8_SA(b, h) + aoff + m * 2048 + k * 1024); } while (0)
; #define PG8_LDB(dst, b, h) do { _Pragma("unroll") for (int n = 0; n < 2; ++n) _Pragma("unroll") for (int k = 0; k < 2; ++k) dst[n][k] = *(const PG8_LAS bf16x8*)(lds + PG8_SB(b, h) + boff + n * 2048 + k * 1024); } while (0)
; #define PG8_MMA(ai, bj, At, Bt) do { __builtin_amdgcn_s_setprio(1); _Pragma("unroll") for (int m = 0; m < 4; ++m) _Pragma("unroll") for (int n = 0; n < 2; ++n) _Pragma("unroll") for (int k = 0; k < 2; ++k) \
;         acc[ai][bj][m][n] = __builtin_amdgcn_mfma_f32_16x16x32_bf16(Bt[n][k], At[m][k], acc[ai][bj][m][n], 0, 0, 0); __builtin_amdgcn_s_setprio(0); } while (0)
; #define PG8_WAIT_V(n) asm volatile("s_waitcnt vmcnt(" #n ")" ::: "memory")
; template <class Epi, class Sched, bool ALIGN_EPI = false, bool SP2 = false>
; __device__ __forceinline__ void gemm_phase(PG8_LAS unsigned char* lds, const Gemm g, const Sched& S, const Epi& E) {
;     ...
;             PG8_LDB(B0, 0, 0); PG8_LDB(B1, 0, 1); PG8_SCHED; PG8_LDA(At, 0, 0); PG8_STAGE(PG8_SA(1, 1), a1 + hstep, voffA);
;             PG8_WAIT_V(8); PG8_WAIT_L(0); PG8_BAR; PG8_MMA(0, 0, At, B0); PG8_MMA(0, 1, At, B1); PG8_BAR; PG8_SCHED;
;             PG8_LDA(At, 0, 1); PG8_STAGE(PG8_SB(0, 0), b2, voffB); PG8_STAGE(PG8_SB(0, 1), b2 + hstep, voffB); PG8_STAGE(PG8_SA(0, 0), a2, voffA);
;             PG8_WAIT_V(8); PG8_WAIT_L(0); PG8_BAR; PG8_MMA(1, 0, At, B0); PG8_MMA(1, 1, At, B1); PG8_BAR; PG8_SCHED;
;             PG8_LDB(B0, 1, 0); PG8_LDB(B1, 1, 1); PG8_SCHED; PG8_LDA(At, 1, 0); PG8_STAGE(PG8_SA(0, 1), a2 + hstep, voffA);
;             PG8_WAIT_V(8); PG8_WAIT_L(0); PG8_BAR; PG8_MMA(0, 0, At, B0); PG8_MMA(0, 1, At, B1); PG8_BAR; PG8_SCHED;
;             PG8_LDA(At, 1, 1); PG8_STAGE(PG8_SB(1, 0), b3, voffB); PG8_STAGE(PG8_SB(1, 1), b3 + hstep, voffB); PG8_STAGE(PG8_SA(1, 0), a3, voffA);
;             PG8_WAIT_V(8); PG8_WAIT_L(0); PG8_BAR; PG8_MMA(1, 0, At, B0); PG8_MMA(1, 1, At, B1); PG8_BAR; PG8_SCHED;
	s_setprio 0
	s_waitcnt lgkmcnt(0)
	v_mfma_f32_16x16x32_bf16 v[60:63], v[130:133], v[172:175], v[60:63]
	v_mfma_f32_16x16x32_bf16 v[56:59], v[138:141], v[172:175], v[56:59]
	v_mfma_f32_16x16x32_bf16 v[44:47], v[130:133], v[180:183], v[44:47]
	v_mfma_f32_16x16x32_bf16 v[40:43], v[138:141], v[180:183], v[40:43]
	v_mfma_f32_16x16x32_bf16 v[28:31], v[130:133], v[188:191], v[28:31]
	v_mfma_f32_16x16x32_bf16 v[24:27], v[138:141], v[188:191], v[24:27]
	v_mfma_f32_16x16x32_bf16 v[12:15], v[130:133], v[196:199], v[12:15]
	v_mfma_f32_16x16x32_bf16 v[8:11], v[138:141], v[196:199], v[8:11]
	v_mfma_f32_16x16x32_bf16 v[60:63], v[134:137], v[176:179], v[60:63]
	v_mfma_f32_16x16x32_bf16 v[56:59], v[142:145], v[176:179], v[56:59]
	v_mfma_f32_16x16x32_bf16 v[44:47], v[134:137], v[184:187], v[44:47]
	v_mfma_f32_16x16x32_bf16 v[40:43], v[142:145], v[184:187], v[40:43]
	v_mfma_f32_16x16x32_bf16 v[28:31], v[134:137], v[192:195], v[28:31]
	v_mfma_f32_16x16x32_bf16 v[24:27], v[142:145], v[192:195], v[24:27]
	v_mfma_f32_16x16x32_bf16 v[12:15], v[134:137], v[204:207], v[12:15]
	v_mfma_f32_16x16x32_bf16 v[8:11], v[142:145], v[204:207], v[8:11]
	v_mfma_f32_16x16x32_bf16 v[52:55], v[156:159], v[172:175], v[52:55]
	v_mfma_f32_16x16x32_bf16 v[48:51], v[164:167], v[172:175], v[48:51]
	v_mfma_f32_16x16x32_bf16 v[36:39], v[156:159], v[180:183], v[36:39]
	v_mfma_f32_16x16x32_bf16 v[32:35], v[164:167], v[180:183], v[32:35]
	v_mfma_f32_16x16x32_bf16 v[20:23], v[156:159], v[188:191], v[20:23]
	v_mfma_f32_16x16x32_bf16 v[16:19], v[164:167], v[188:191], v[16:19]
	v_mfma_f32_16x16x32_bf16 v[4:7], v[156:159], v[196:199], v[4:7]
	v_mfma_f32_16x16x32_bf16 v[0:3], v[164:167], v[196:199], v[0:3]
	v_mfma_f32_16x16x32_bf16 v[52:55], v[160:163], v[176:179], v[52:55]
	v_mfma_f32_16x16x32_bf16 v[48:51], v[168:171], v[176:179], v[48:51]
	v_mfma_f32_16x16x32_bf16 v[36:39], v[160:163], v[184:187], v[36:39]
	v_mfma_f32_16x16x32_bf16 v[32:35], v[168:171], v[184:187], v[32:35]
	v_mfma_f32_16x16x32_bf16 v[20:23], v[160:163], v[192:195], v[20:23]
	v_mfma_f32_16x16x32_bf16 v[16:19], v[168:171], v[192:195], v[16:19]
	v_mfma_f32_16x16x32_bf16 v[4:7], v[160:163], v[204:207], v[4:7]
	v_mfma_f32_16x16x32_bf16 v[0:3], v[168:171], v[204:207], v[0:3]
	s_barrier
	s_setprio 1
	s_add_i32 s8, 0, 0x18000
	s_add_i32 s85, 0, 0x1c000
	v_add_u32_e32 v142, s8, v201
	v_add_u32_e32 v168, s85, v201
	ds_read_b128 v[130:133], v142
	ds_read_b128 v[134:137], v142 offset:1024
	ds_read_b128 v[138:141], v142 offset:2048
	ds_read_b128 v[142:145], v142 offset:3072
	ds_read_b128 v[156:159], v168
	ds_read_b128 v[160:163], v168 offset:1024
	ds_read_b128 v[164:167], v168 offset:2048
	ds_read_b128 v[168:171], v168 offset:3072
	s_add_u32 s64, s64, 0xb0000
	s_addc_u32 s65, s65, 0
	s_mov_b32 m0, s19
	v_lshl_add_u64 v[228:229], s[64:65], 0, v[150:151]
	ds_read_b128 v[172:175], v203 offset:32768
	ds_read_b128 v[176:179], v203 offset:33792
	ds_read_b128 v[180:183], v203 offset:34816
	ds_read_b128 v[184:187], v203 offset:35840
	ds_read_b128 v[188:191], v203 offset:36864
	ds_read_b128 v[192:195], v203 offset:37888
	ds_read_b128 v[196:199], v203 offset:38912
	ds_read_b128 v[204:207], v203 offset:39936
	global_load_lds_dwordx4 v[228:229], off
	v_lshl_add_u64 v[228:229], s[64:65], 0, v[148:149]
	s_mov_b32 m0, s20
	s_nop 0
	global_load_lds_dwordx4 v[228:229], off
	s_waitcnt vmcnt(8)
	s_waitcnt lgkmcnt(0)
	s_barrier
	s_setprio 0
	s_waitcnt lgkmcnt(0)
	v_mfma_f32_16x16x32_bf16 v[124:127], v[130:133], v[172:175], v[124:127]
	v_mfma_f32_16x16x32_bf16 v[120:123], v[138:141], v[172:175], v[120:123]
	v_mfma_f32_16x16x32_bf16 v[108:111], v[130:133], v[180:183], v[108:111]
	v_mfma_f32_16x16x32_bf16 v[104:107], v[138:141], v[180:183], v[104:107]
	v_mfma_f32_16x16x32_bf16 v[92:95], v[130:133], v[188:191], v[92:95]
	v_mfma_f32_16x16x32_bf16 v[88:91], v[138:141], v[188:191], v[88:91]
	v_mfma_f32_16x16x32_bf16 v[76:79], v[130:133], v[196:199], v[76:79]
	v_mfma_f32_16x16x32_bf16 v[72:75], v[138:141], v[196:199], v[72:75]
	v_mfma_f32_16x16x32_bf16 v[124:127], v[134:137], v[176:179], v[124:127]
	v_mfma_f32_16x16x32_bf16 v[120:123], v[142:145], v[176:179], v[120:123]
	v_mfma_f32_16x16x32_bf16 v[108:111], v[134:137], v[184:187], v[108:111]
	v_mfma_f32_16x16x32_bf16 v[104:107], v[142:145], v[184:187], v[104:107]
	v_mfma_f32_16x16x32_bf16 v[92:95], v[134:137], v[192:195], v[92:95]
	v_mfma_f32_16x16x32_bf16 v[88:91], v[142:145], v[192:195], v[88:91]
	v_mfma_f32_16x16x32_bf16 v[76:79], v[134:137], v[204:207], v[76:79]
	v_mfma_f32_16x16x32_bf16 v[72:75], v[142:145], v[204:207], v[72:75]
	v_mfma_f32_16x16x32_bf16 v[116:119], v[156:159], v[172:175], v[116:119]
	v_mfma_f32_16x16x32_bf16 v[112:115], v[164:167], v[172:175], v[112:115]
	v_mfma_f32_16x16x32_bf16 v[100:103], v[156:159], v[180:183], v[100:103]
	v_mfma_f32_16x16x32_bf16 v[96:99], v[164:167], v[180:183], v[96:99]
	v_mfma_f32_16x16x32_bf16 v[84:87], v[156:159], v[188:191], v[84:87]
	v_mfma_f32_16x16x32_bf16 v[80:83], v[164:167], v[188:191], v[80:83]
	v_mfma_f32_16x16x32_bf16 v[68:71], v[156:159], v[196:199], v[68:71]
	v_mfma_f32_16x16x32_bf16 v[64:67], v[164:167], v[196:199], v[64:67]
	v_mfma_f32_16x16x32_bf16 v[116:119], v[160:163], v[176:179], v[116:119]
	v_mfma_f32_16x16x32_bf16 v[112:115], v[168:171], v[176:179], v[112:115]
	v_mfma_f32_16x16x32_bf16 v[100:103], v[160:163], v[184:187], v[100:103]
	v_mfma_f32_16x16x32_bf16 v[96:99], v[168:171], v[184:187], v[96:99]
	v_mfma_f32_16x16x32_bf16 v[84:87], v[160:163], v[192:195], v[84:87]
	v_mfma_f32_16x16x32_bf16 v[80:83], v[168:171], v[192:195], v[80:83]
	v_mfma_f32_16x16x32_bf16 v[68:71], v[160:163], v[204:207], v[68:71]
	v_mfma_f32_16x16x32_bf16 v[64:67], v[168:171], v[204:207], v[64:67]
	s_barrier
; #define PG8_STAGE(bufoff, gbase, voff) do { _Pragma("unroll") for (int _i = 0; _i < 2; ++_i) \
;         __builtin_amdgcn_global_load_lds((const unsigned*)((const char*)(gbase) + (voff)[_i]), (PG8_LAS unsigned*)(lds + (bufoff) + ldsw + _i * 8192), 16, 0, 0); } while (0)
; #define PG8_LDA(dst, b, h) do { _Pragma("unroll") for (int m = 0; m < 4; ++m) _Pragma("unroll") for (int k = 0; k < 2; ++k) dst[m][k] = *(const PG8_LAS bf16x8*)(lds + PG8_SA(b, h) + aoff + m * 2048 + k * 1024); } while (0)
; #define PG8_LDB(dst, b, h) do { _Pragma("unroll") for (int n = 0; n < 2; ++n) _Pragma("unroll") for (int k = 0; k < 2; ++k) dst[n][k] = *(const PG8_LAS bf16x8*)(lds + PG8_SB(b, h) + boff + n * 2048 + k * 1024); } while (0)
; #define PG8_MMA(ai, bj, At, Bt) do { __builtin_amdgcn_s_setprio(1); _Pragma("unroll") for (int m = 0; m < 4; ++m) _Pragma("unroll") for (int n = 0; n < 2; ++n) _Pragma("unroll") for (int k = 0; k < 2; ++k) \
;         acc[ai][bj][m][n] = __builtin_amdgcn_mfma_f32_16x16x32_bf16(Bt[n][k], At[m][k], acc[ai][bj][m][n], 0, 0, 0); __builtin_amdgcn_s_setprio(0); } while (0)
; template <class Epi, class Sched, bool ALIGN_EPI = false, bool SP2 = false>
; __device__ __forceinline__ void gemm_phase(PG8_LAS unsigned char* lds, const Gemm g, const Sched& S, const Epi& E) {
;     ...
;             PG8_LDB(B0, 0, 0); PG8_LDB(B1, 0, 1); PG8_SCHED; PG8_LDA(At, 0, 0); PG8_STAGE(PG8_SA(1, 1), a1 + hstep, voffA);
;             PG8_WAIT_V(8); PG8_WAIT_L(0); PG8_BAR; PG8_MMA(0, 0, At, B0); PG8_MMA(0, 1, At, B1); PG8_BAR; PG8_SCHED;
;             PG8_LDA(At, 0, 1); PG8_STAGE(PG8_SB(0, 0), b2, voffB); PG8_STAGE(PG8_SB(0, 1), b2 + hstep, voffB); PG8_STAGE(PG8_SA(0, 0), a2, voffA);
;             PG8_WAIT_V(8); PG8_WAIT_L(0); PG8_BAR; PG8_MMA(1, 0, At, B0); PG8_MMA(1, 1, At, B1); PG8_BAR; PG8_SCHED;
;             PG8_LDB(B0, 1, 0); PG8_LDB(B1, 1, 1); PG8_SCHED; PG8_LDA(At, 1, 0); PG8_STAGE(PG8_SA(0, 1), a2 + hstep, voffA);
;             PG8_WAIT_V(8); PG8_WAIT_L(0); PG8_BAR; PG8_MMA(0, 0, At, B0); PG8_MMA(0, 1, At, B1); PG8_BAR; PG8_SCHED;
;             PG8_LDA(At, 1, 1); PG8_STAGE(PG8_SB(1, 0), b3, voffB); PG8_STAGE(PG8_SB(1, 1), b3 + hstep, voffB); PG8_STAGE(PG8_SA(1, 0), a3, voffA);
;             PG8_WAIT_V(8); PG8_WAIT_L(0); PG8_BAR; PG8_MMA(1, 0, At, B0); PG8_MMA(1, 1, At, B1); PG8_BAR; PG8_SCHED;
;     ...
;         if constexpr (ALIGN_EPI) { if (wr == 0) PG8_BAR; }
	s_setprio 1
	s_add_i32 s8, s8, s14
	v_lshl_add_u64 v[208:209], v[208:209], 0, s[90:91]
	s_mov_b32 m0, s8
	ds_read_b128 v[172:175], v203 offset:49152
	ds_read_b128 v[176:179], v203 offset:50176
	ds_read_b128 v[180:183], v203 offset:51200
	ds_read_b128 v[184:187], v203 offset:52224
	ds_read_b128 v[188:191], v203 offset:53248
	ds_read_b128 v[192:195], v203 offset:54272
	ds_read_b128 v[196:199], v203 offset:55296
	ds_read_b128 v[204:207], v203 offset:56320
	global_load_lds_dwordx4 v[208:209], off
	s_add_i32 m0, s8, 0x2000
	s_add_u32 s46, s46, 0xb0080
	v_lshl_add_u64 v[208:209], v[210:211], 0, s[90:91]
	s_addc_u32 s47, s47, 0
	s_add_i32 s8, s85, s14
	global_load_lds_dwordx4 v[208:209], off
	v_lshl_add_u64 v[208:209], s[46:47], 0, v[128:129]
	s_mov_b32 m0, s8
	s_nop 0
	global_load_lds_dwordx4 v[208:209], off
	v_lshl_add_u64 v[208:209], s[46:47], 0, v[146:147]
	s_add_i32 m0, s8, 0x2000
	s_nop 0
	global_load_lds_dwordx4 v[208:209], off
	v_lshl_add_u64 v[208:209], v[214:215], 0, s[90:91]
	s_mov_b32 m0, s29
	s_nop 0
	global_load_lds_dwordx4 v[208:209], off
	v_lshl_add_u64 v[208:209], v[222:223], 0, s[90:91]
	s_mov_b32 m0, s30
	s_nop 0
	global_load_lds_dwordx4 v[208:209], off
	s_waitcnt vmcnt(8)
	s_waitcnt lgkmcnt(0)
	s_barrier
	s_setprio 0
	s_waitcnt lgkmcnt(0)
	v_mfma_f32_16x16x32_bf16 v[60:63], v[130:133], v[172:175], v[60:63]
	v_mfma_f32_16x16x32_bf16 v[56:59], v[138:141], v[172:175], v[56:59]
	v_mfma_f32_16x16x32_bf16 v[44:47], v[130:133], v[180:183], v[44:47]
	v_mfma_f32_16x16x32_bf16 v[40:43], v[138:141], v[180:183], v[40:43]
	v_mfma_f32_16x16x32_bf16 v[28:31], v[130:133], v[188:191], v[28:31]
	v_mfma_f32_16x16x32_bf16 v[24:27], v[138:141], v[188:191], v[24:27]
	v_mfma_f32_16x16x32_bf16 v[12:15], v[130:133], v[196:199], v[12:15]
	v_mfma_f32_16x16x32_bf16 v[8:11], v[138:141], v[196:199], v[8:11]
	v_mfma_f32_16x16x32_bf16 v[60:63], v[134:137], v[176:179], v[60:63]
	v_mfma_f32_16x16x32_bf16 v[56:59], v[142:145], v[176:179], v[56:59]
	v_mfma_f32_16x16x32_bf16 v[44:47], v[134:137], v[184:187], v[44:47]
	v_mfma_f32_16x16x32_bf16 v[40:43], v[142:145], v[184:187], v[40:43]
	v_mfma_f32_16x16x32_bf16 v[28:31], v[134:137], v[192:195], v[28:31]
	v_mfma_f32_16x16x32_bf16 v[24:27], v[142:145], v[192:195], v[24:27]
	v_mfma_f32_16x16x32_bf16 v[12:15], v[134:137], v[204:207], v[12:15]
	v_mfma_f32_16x16x32_bf16 v[8:11], v[142:145], v[204:207], v[8:11]
	v_mfma_f32_16x16x32_bf16 v[52:55], v[156:159], v[172:175], v[52:55]
	v_mfma_f32_16x16x32_bf16 v[48:51], v[164:167], v[172:175], v[48:51]
	v_mfma_f32_16x16x32_bf16 v[36:39], v[156:159], v[180:183], v[36:39]
	v_mfma_f32_16x16x32_bf16 v[32:35], v[164:167], v[180:183], v[32:35]
	v_mfma_f32_16x16x32_bf16 v[20:23], v[156:159], v[188:191], v[20:23]
	v_mfma_f32_16x16x32_bf16 v[16:19], v[164:167], v[188:191], v[16:19]
	v_mfma_f32_16x16x32_bf16 v[4:7], v[156:159], v[196:199], v[4:7]
	v_mfma_f32_16x16x32_bf16 v[0:3], v[164:167], v[196:199], v[0:3]
	v_mfma_f32_16x16x32_bf16 v[52:55], v[160:163], v[176:179], v[52:55]
	v_mfma_f32_16x16x32_bf16 v[48:51], v[168:171], v[176:179], v[48:51]
	v_mfma_f32_16x16x32_bf16 v[36:39], v[160:163], v[184:187], v[36:39]
	v_mfma_f32_16x16x32_bf16 v[32:35], v[168:171], v[184:187], v[32:35]
	v_mfma_f32_16x16x32_bf16 v[20:23], v[160:163], v[192:195], v[20:23]
	v_mfma_f32_16x16x32_bf16 v[16:19], v[168:171], v[192:195], v[16:19]
	v_mfma_f32_16x16x32_bf16 v[4:7], v[160:163], v[204:207], v[4:7]
	v_mfma_f32_16x16x32_bf16 v[0:3], v[168:171], v[204:207], v[0:3]
	s_barrier
	s_setprio 1
	s_add_i32 s84, s84, 2
	s_add_u32 s36, s36, 0x100
	s_addc_u32 s37, s37, 0
	s_cmp_gt_u32 s84, 41
	s_mov_b64 s[96:97], s[42:43]
	s_cbranch_scc0 .LBB0_995
	s_setprio 0
	s_and_b64 vcc, exec, s[62:63]
	s_cbranch_vccz .LBB0_998
	s_barrier
